# fused epilogue: packed f32 ops split into scalar fma/mul pairs
# speedup vs baseline: 1.0093x; 1.0036x over previous
; #define PG8_STAGE(bufoff, gbase, voff) do { _Pragma("unroll") for (int _i = 0; _i < 2; ++_i) \
;         __builtin_amdgcn_global_load_lds((const unsigned*)((const char*)(gbase) + (voff)[_i]), (LAS unsigned*)(lds + (bufoff) + ldsw + _i * 8192), 16, 0, 0); } while (0)
; #define PG8_LDA(dst, b, h) do { _Pragma("unroll") for (int m = 0; m < 4; ++m) _Pragma("unroll") for (int k = 0; k < 2; ++k) dst[m][k] = *(const LAS bf16x8*)(lds + PG8_SA(b, h) + aoff + m * 2048 + k * 1024); } while (0)
; #define PG8_LDB(dst, b, h) do { _Pragma("unroll") for (int n = 0; n < 2; ++n) _Pragma("unroll") for (int k = 0; k < 2; ++k) dst[n][k] = *(const LAS bf16x8*)(lds + PG8_SB(b, h) + boff + n * 2048 + k * 1024); } while (0)
; #define PG8_MMA(ai, bj, At, Bt) do { __builtin_amdgcn_s_setprio(1); _Pragma("unroll") for (int m = 0; m < 4; ++m) _Pragma("unroll") for (int n = 0; n < 2; ++n) _Pragma("unroll") for (int k = 0; k < 2; ++k) \
;         acc[ai][bj][m][n] = __builtin_amdgcn_mfma_f32_16x16x32_bf16(Bt[n][k], At[m][k], acc[ai][bj][m][n], 0, 0, 0); __builtin_amdgcn_s_setprio(0); } while (0)
; #define PG8_WAIT_V(n) asm volatile("s_waitcnt vmcnt(" #n ")" ::: "memory")
; #define PG8_BAR __builtin_amdgcn_s_barrier()
; template <class F>
; DI void gemm_phase(const int tid, LAS unsigned char* lds, const bf16_t* Ap, int lda, const bf16_t* Bp, int ldb, int M, int N, int K, int G, int c, bool direct, const F& E) {
;     ...
;         for (int t = 0; t < nt; t += 2) {
;             const bool last = (t == nt - 2);
;             const char* a1 = cA + (size_t)(t + 1) * kstep;
;             const char* a2 = last ? nA : cA + (size_t)(t + 2) * kstep; const char* b2 = last ? nB : cB + (size_t)(t + 2) * kstep;
;             const char* a3 = a2 + kstep; const char* b3 = b2 + kstep;
;             PG8_LDB(B0, 0, 0); PG8_SCHED; PG8_LDA(At, 0, 0); PG8_STAGE(PG8_SA(1, 1), a1 + hsA, voffA);
;             PG8_WAIT_L(8); PG8_BAR; PG8_WAIT_L(0); PG8_MMA(0, 0, At, B0); PG8_BAR; PG8_SCHED;
;             PG8_LDB(B1, 0, 1); PG8_STAGE(PG8_SB(0, 0), b2, voffB);
;             PG8_BAR; PG8_WAIT_L(0); PG8_MMA(0, 1, At, B1); PG8_BAR;
;             PG8_LDA(At, 0, 1); PG8_STAGE(PG8_SA(0, 0), a2, voffA);
;             PG8_BAR; PG8_WAIT_L(0); PG8_MMA(1, 0, At, B0); PG8_BAR; PG8_SCHED;
;             PG8_STAGE(PG8_SB(0, 1), b2 + hsB, voffB);
;             PG8_WAIT_V(6); PG8_BAR; PG8_MMA(1, 1, At, B1); PG8_BAR;
.LBB0_657:
	s_add_i32 s81, s76, 2
	s_add_u32 s78, s74, 0x80
	s_addc_u32 s77, s75, 0
	s_add_i32 s82, 0, 0x10000
	v_add_u32_e32 v140, s82, v189
	ds_read_b128 v[128:131], v140
	ds_read_b128 v[132:135], v140 offset:1024
	ds_read_b128 v[136:139], v140 offset:2048
	ds_read_b128 v[140:143], v140 offset:3072
	s_cmp_eq_u32 s67, s76
	s_cselect_b32 s76, s0, s78
	s_cselect_b32 s77, s1, s77
	s_cselect_b32 s79, s5, s80
	s_cselect_b32 s78, s4, s71
	v_lshl_add_u64 v[208:209], s[74:75], 0, v[204:205]
	s_add_i32 m0, s28, 0xc000
	ds_read_b128 v[144:147], v197
	ds_read_b128 v[148:151], v197 offset:1024
	ds_read_b128 v[152:155], v197 offset:2048
	ds_read_b128 v[156:159], v197 offset:3072
	ds_read_b128 v[160:163], v197 offset:4096
	ds_read_b128 v[164:167], v197 offset:5120
	ds_read_b128 v[168:171], v197 offset:6144
	ds_read_b128 v[172:175], v197 offset:7168
	global_load_lds_dwordx4 v[208:209], off
	v_lshl_add_u64 v[208:209], s[74:75], 0, v[206:207]
	s_add_i32 m0, s28, 0xe000
	s_nop 0
	global_load_lds_dwordx4 v[208:209], off
	s_waitcnt lgkmcnt(8)
	s_barrier
	s_waitcnt lgkmcnt(0)
	s_setprio 1
	s_waitcnt lgkmcnt(0)
	v_mfma_f32_16x16x32_bf16 v[124:127], v[128:131], v[144:147], v[124:127]
	v_mfma_f32_16x16x32_bf16 v[120:123], v[136:139], v[144:147], v[120:123]
	v_mfma_f32_16x16x32_bf16 v[116:119], v[128:131], v[152:155], v[116:119]
	v_mfma_f32_16x16x32_bf16 v[104:107], v[136:139], v[152:155], v[104:107]
	v_mfma_f32_16x16x32_bf16 v[100:103], v[128:131], v[160:163], v[100:103]
	v_mfma_f32_16x16x32_bf16 v[88:91], v[136:139], v[160:163], v[88:91]
	v_mfma_f32_16x16x32_bf16 v[84:87], v[128:131], v[168:171], v[84:87]
	v_mfma_f32_16x16x32_bf16 v[72:75], v[136:139], v[168:171], v[72:75]
	v_mfma_f32_16x16x32_bf16 v[124:127], v[132:135], v[148:151], v[124:127]
	v_mfma_f32_16x16x32_bf16 v[120:123], v[140:143], v[148:151], v[120:123]
	v_mfma_f32_16x16x32_bf16 v[116:119], v[132:135], v[156:159], v[116:119]
	v_mfma_f32_16x16x32_bf16 v[104:107], v[140:143], v[156:159], v[104:107]
	v_mfma_f32_16x16x32_bf16 v[100:103], v[132:135], v[164:167], v[100:103]
	v_mfma_f32_16x16x32_bf16 v[88:91], v[140:143], v[164:167], v[88:91]
	v_mfma_f32_16x16x32_bf16 v[84:87], v[132:135], v[172:175], v[84:87]
	v_mfma_f32_16x16x32_bf16 v[72:75], v[140:143], v[172:175], v[72:75]
	s_setprio 0
	s_barrier
	s_add_i32 s82, s82, s27
	v_add_u32_e32 v180, s95, v189
	v_lshl_add_u64 v[224:225], s[78:79], 0, v[178:179]
	s_mov_b32 m0, s82
	ds_read_b128 v[208:211], v180
	ds_read_b128 v[212:215], v180 offset:1024
	ds_read_b128 v[216:219], v180 offset:2048
	ds_read_b128 v[220:223], v180 offset:3072
	global_load_lds_dwordx4 v[224:225], off
	v_lshl_add_u64 v[226:227], s[78:79], 0, v[186:187]
	s_add_i32 m0, s82, 0x2000
	s_nop 0
	global_load_lds_dwordx4 v[226:227], off
	s_barrier
	s_waitcnt lgkmcnt(0)
	s_setprio 1
	s_waitcnt lgkmcnt(0)
	v_mfma_f32_16x16x32_bf16 v[112:115], v[208:211], v[144:147], v[112:115]
	v_mfma_f32_16x16x32_bf16 v[108:111], v[216:219], v[144:147], v[108:111]
	v_mfma_f32_16x16x32_bf16 v[96:99], v[208:211], v[152:155], v[96:99]
	v_mfma_f32_16x16x32_bf16 v[92:95], v[216:219], v[152:155], v[92:95]
	v_mfma_f32_16x16x32_bf16 v[80:83], v[208:211], v[160:163], v[80:83]
	v_mfma_f32_16x16x32_bf16 v[76:79], v[216:219], v[160:163], v[76:79]
	v_mfma_f32_16x16x32_bf16 v[68:71], v[208:211], v[168:171], v[68:71]
	v_mfma_f32_16x16x32_bf16 v[64:67], v[216:219], v[168:171], v[64:67]
	v_mfma_f32_16x16x32_bf16 v[112:115], v[212:215], v[148:151], v[112:115]
	v_mfma_f32_16x16x32_bf16 v[108:111], v[220:223], v[148:151], v[108:111]
	v_mfma_f32_16x16x32_bf16 v[96:99], v[212:215], v[156:159], v[96:99]
	v_mfma_f32_16x16x32_bf16 v[92:95], v[220:223], v[156:159], v[92:95]
	v_mfma_f32_16x16x32_bf16 v[80:83], v[212:215], v[164:167], v[80:83]
	v_mfma_f32_16x16x32_bf16 v[76:79], v[220:223], v[164:167], v[76:79]
	v_mfma_f32_16x16x32_bf16 v[68:71], v[212:215], v[172:175], v[68:71]
	v_mfma_f32_16x16x32_bf16 v[64:67], v[220:223], v[172:175], v[64:67]
	s_setprio 0
	s_mov_b32 m0, s28
	v_lshl_add_u64 v[228:229], s[76:77], 0, v[176:177]
	s_barrier
	ds_read_b128 v[144:147], v197 offset:16384
	ds_read_b128 v[148:151], v197 offset:17408
	ds_read_b128 v[152:155], v197 offset:18432
	ds_read_b128 v[156:159], v197 offset:19456
	ds_read_b128 v[160:163], v197 offset:20480
	ds_read_b128 v[164:167], v197 offset:21504
	ds_read_b128 v[168:171], v197 offset:22528
	ds_read_b128 v[172:175], v197 offset:23552
	global_load_lds_dwordx4 v[228:229], off
	v_lshl_add_u64 v[242:243], s[76:77], 0, v[184:185]
	s_mov_b32 m0, s34
	s_nop 0
	global_load_lds_dwordx4 v[242:243], off
	s_barrier
	s_waitcnt lgkmcnt(0)
	s_setprio 1
	s_waitcnt lgkmcnt(0)
	v_mfma_f32_16x16x32_bf16 v[60:63], v[128:131], v[144:147], v[60:63]
	v_mfma_f32_16x16x32_bf16 v[56:59], v[136:139], v[144:147], v[56:59]
	v_mfma_f32_16x16x32_bf16 v[52:55], v[128:131], v[152:155], v[52:55]
	v_mfma_f32_16x16x32_bf16 v[40:43], v[136:139], v[152:155], v[40:43]
	v_mfma_f32_16x16x32_bf16 v[36:39], v[128:131], v[160:163], v[36:39]
	v_mfma_f32_16x16x32_bf16 v[16:19], v[136:139], v[160:163], v[16:19]
	v_mfma_f32_16x16x32_bf16 v[12:15], v[128:131], v[168:171], v[12:15]
	v_mfma_f32_16x16x32_bf16 v[0:3], v[136:139], v[168:171], v[0:3]
	v_mfma_f32_16x16x32_bf16 v[60:63], v[132:135], v[148:151], v[60:63]
	v_mfma_f32_16x16x32_bf16 v[56:59], v[140:143], v[148:151], v[56:59]
	v_mfma_f32_16x16x32_bf16 v[52:55], v[132:135], v[156:159], v[52:55]
	v_mfma_f32_16x16x32_bf16 v[40:43], v[140:143], v[156:159], v[40:43]
	v_mfma_f32_16x16x32_bf16 v[36:39], v[132:135], v[164:167], v[36:39]
	v_mfma_f32_16x16x32_bf16 v[16:19], v[140:143], v[164:167], v[16:19]
	v_mfma_f32_16x16x32_bf16 v[12:15], v[132:135], v[172:175], v[12:15]
	v_mfma_f32_16x16x32_bf16 v[0:3], v[140:143], v[172:175], v[0:3]
	s_setprio 0
	s_barrier
; #define PG8_STAGE(bufoff, gbase, voff) do { _Pragma("unroll") for (int _i = 0; _i < 2; ++_i) \
;         __builtin_amdgcn_global_load_lds((const unsigned*)((const char*)(gbase) + (voff)[_i]), (LAS unsigned*)(lds + (bufoff) + ldsw + _i * 8192), 16, 0, 0); } while (0)
; #define PG8_LDA(dst, b, h) do { _Pragma("unroll") for (int m = 0; m < 4; ++m) _Pragma("unroll") for (int k = 0; k < 2; ++k) dst[m][k] = *(const LAS bf16x8*)(lds + PG8_SA(b, h) + aoff + m * 2048 + k * 1024); } while (0)
; #define PG8_LDB(dst, b, h) do { _Pragma("unroll") for (int n = 0; n < 2; ++n) _Pragma("unroll") for (int k = 0; k < 2; ++k) dst[n][k] = *(const LAS bf16x8*)(lds + PG8_SB(b, h) + boff + n * 2048 + k * 1024); } while (0)
; #define PG8_MMA(ai, bj, At, Bt) do { __builtin_amdgcn_s_setprio(1); _Pragma("unroll") for (int m = 0; m < 4; ++m) _Pragma("unroll") for (int n = 0; n < 2; ++n) _Pragma("unroll") for (int k = 0; k < 2; ++k) \
;         acc[ai][bj][m][n] = __builtin_amdgcn_mfma_f32_16x16x32_bf16(Bt[n][k], At[m][k], acc[ai][bj][m][n], 0, 0, 0); __builtin_amdgcn_s_setprio(0); } while (0)
; #define PG8_WAIT_V(n) asm volatile("s_waitcnt vmcnt(" #n ")" ::: "memory")
; #define PG8_WAIT_L(n) asm volatile("s_waitcnt lgkmcnt(" #n ")" ::: "memory")
; #define PG8_BAR __builtin_amdgcn_s_barrier()
; #define PG8_SCHED __builtin_amdgcn_sched_barrier(0)
; template <class F>
; DI void gemm_phase(const int tid, LAS unsigned char* lds, const bf16_t* Ap, int lda, const bf16_t* Bp, int ldb, int M, int N, int K, int G, int c, bool direct, const F& E) {
;     ...
;             PG8_STAGE(PG8_SB(0, 1), b2 + hsB, voffB);
;             PG8_WAIT_V(6); PG8_BAR; PG8_MMA(1, 1, At, B1); PG8_BAR;
;             PG8_LDB(B0, 1, 0); PG8_SCHED; PG8_LDA(At, 1, 0); PG8_STAGE(PG8_SA(0, 1), a2 + hsA, voffA);
;             PG8_WAIT_L(8); PG8_BAR; PG8_WAIT_L(0); PG8_MMA(0, 0, At, B0); PG8_BAR; PG8_SCHED;
;             PG8_LDB(B1, 1, 1); PG8_STAGE(PG8_SB(1, 0), b3, voffB);
;             PG8_BAR; PG8_WAIT_L(0); PG8_MMA(0, 1, At, B1); PG8_BAR;
;             PG8_LDA(At, 1, 1); PG8_STAGE(PG8_SA(1, 0), a3, voffA);
;             PG8_BAR; PG8_WAIT_L(0); PG8_MMA(1, 0, At, B0); PG8_BAR; PG8_SCHED;
	s_add_u32 s78, s78, s46
	s_addc_u32 s79, s79, 0
	s_add_i32 s82, s95, s27
	v_lshl_add_u64 v[244:245], s[78:79], 0, v[178:179]
	s_mov_b32 m0, s82
	v_lshl_add_u64 v[246:247], s[78:79], 0, v[186:187]
	global_load_lds_dwordx4 v[244:245], off
	s_add_i32 m0, s82, 0x2000
	s_nop 0
	global_load_lds_dwordx4 v[246:247], off
	s_waitcnt vmcnt(6)
	s_barrier
	s_setprio 1
	v_mfma_f32_16x16x32_bf16 v[48:51], v[208:211], v[144:147], v[48:51]
	v_mfma_f32_16x16x32_bf16 v[44:47], v[216:219], v[144:147], v[44:47]
	v_mfma_f32_16x16x32_bf16 v[24:27], v[208:211], v[152:155], v[24:27]
	v_mfma_f32_16x16x32_bf16 v[20:23], v[216:219], v[152:155], v[20:23]
	v_mfma_f32_16x16x32_bf16 v[28:31], v[208:211], v[160:163], v[28:31]
	v_mfma_f32_16x16x32_bf16 v[32:35], v[216:219], v[160:163], v[32:35]
	v_mfma_f32_16x16x32_bf16 v[8:11], v[208:211], v[168:171], v[8:11]
	v_mfma_f32_16x16x32_bf16 v[4:7], v[216:219], v[168:171], v[4:7]
	v_mfma_f32_16x16x32_bf16 v[48:51], v[212:215], v[148:151], v[48:51]
	v_mfma_f32_16x16x32_bf16 v[44:47], v[220:223], v[148:151], v[44:47]
	v_mfma_f32_16x16x32_bf16 v[24:27], v[212:215], v[156:159], v[24:27]
	v_mfma_f32_16x16x32_bf16 v[20:23], v[220:223], v[156:159], v[20:23]
	v_mfma_f32_16x16x32_bf16 v[28:31], v[212:215], v[164:167], v[28:31]
	v_mfma_f32_16x16x32_bf16 v[32:35], v[220:223], v[164:167], v[32:35]
	v_mfma_f32_16x16x32_bf16 v[8:11], v[212:215], v[172:175], v[8:11]
	v_mfma_f32_16x16x32_bf16 v[4:7], v[220:223], v[172:175], v[4:7]
	s_setprio 0
	s_add_i32 s78, 0, 0x18000
	v_add_u32_e32 v140, s78, v189
	s_barrier
	ds_read_b128 v[128:131], v140
	ds_read_b128 v[132:135], v140 offset:1024
	ds_read_b128 v[136:139], v140 offset:2048
	ds_read_b128 v[140:143], v140 offset:3072
	s_add_u32 s76, s76, s24
	s_addc_u32 s77, s77, 0
	s_mov_b32 m0, s60
	v_lshl_add_u64 v[208:209], s[76:77], 0, v[176:177]
	ds_read_b128 v[144:147], v197 offset:32768
	ds_read_b128 v[148:151], v197 offset:33792
	ds_read_b128 v[152:155], v197 offset:34816
	ds_read_b128 v[156:159], v197 offset:35840
	ds_read_b128 v[160:163], v197 offset:36864
	ds_read_b128 v[164:167], v197 offset:37888
	ds_read_b128 v[168:171], v197 offset:38912
	ds_read_b128 v[172:175], v197 offset:39936
	global_load_lds_dwordx4 v[208:209], off
	v_lshl_add_u64 v[208:209], s[76:77], 0, v[184:185]
	s_mov_b32 m0, s61
	s_nop 0
	global_load_lds_dwordx4 v[208:209], off
	s_waitcnt lgkmcnt(8)
	s_barrier
	s_waitcnt lgkmcnt(0)
	s_setprio 1
	s_waitcnt lgkmcnt(0)
	v_mfma_f32_16x16x32_bf16 v[124:127], v[128:131], v[144:147], v[124:127]
	v_mfma_f32_16x16x32_bf16 v[120:123], v[136:139], v[144:147], v[120:123]
	v_mfma_f32_16x16x32_bf16 v[116:119], v[128:131], v[152:155], v[116:119]
	v_mfma_f32_16x16x32_bf16 v[104:107], v[136:139], v[152:155], v[104:107]
	v_mfma_f32_16x16x32_bf16 v[100:103], v[128:131], v[160:163], v[100:103]
	v_mfma_f32_16x16x32_bf16 v[88:91], v[136:139], v[160:163], v[88:91]
	v_mfma_f32_16x16x32_bf16 v[84:87], v[128:131], v[168:171], v[84:87]
	v_mfma_f32_16x16x32_bf16 v[72:75], v[136:139], v[168:171], v[72:75]
	v_mfma_f32_16x16x32_bf16 v[124:127], v[132:135], v[148:151], v[124:127]
	v_mfma_f32_16x16x32_bf16 v[120:123], v[140:143], v[148:151], v[120:123]
	v_mfma_f32_16x16x32_bf16 v[116:119], v[132:135], v[156:159], v[116:119]
	v_mfma_f32_16x16x32_bf16 v[104:107], v[140:143], v[156:159], v[104:107]
	v_mfma_f32_16x16x32_bf16 v[100:103], v[132:135], v[164:167], v[100:103]
	v_mfma_f32_16x16x32_bf16 v[88:91], v[140:143], v[164:167], v[88:91]
	v_mfma_f32_16x16x32_bf16 v[84:87], v[132:135], v[172:175], v[84:87]
	v_mfma_f32_16x16x32_bf16 v[72:75], v[140:143], v[172:175], v[72:75]
	s_setprio 0
	s_barrier
	s_add_i32 s76, 0, 0x1c000
	s_add_i32 s77, s78, s27
	v_add_u32_e32 v180, s76, v189
	v_lshl_add_u64 v[224:225], v[224:225], 0, s[30:31]
	s_mov_b32 m0, s77
	ds_read_b128 v[208:211], v180
	ds_read_b128 v[212:215], v180 offset:1024
	ds_read_b128 v[216:219], v180 offset:2048
	ds_read_b128 v[220:223], v180 offset:3072
	global_load_lds_dwordx4 v[224:225], off
	v_lshl_add_u64 v[224:225], v[226:227], 0, s[30:31]
	s_add_i32 m0, s77, 0x2000
	s_nop 0
	global_load_lds_dwordx4 v[224:225], off
	s_barrier
	s_waitcnt lgkmcnt(0)
	s_setprio 1
	s_waitcnt lgkmcnt(0)
	v_mfma_f32_16x16x32_bf16 v[112:115], v[208:211], v[144:147], v[112:115]
	v_mfma_f32_16x16x32_bf16 v[108:111], v[216:219], v[144:147], v[108:111]
	v_mfma_f32_16x16x32_bf16 v[96:99], v[208:211], v[152:155], v[96:99]
	v_mfma_f32_16x16x32_bf16 v[92:95], v[216:219], v[152:155], v[92:95]
	v_mfma_f32_16x16x32_bf16 v[80:83], v[208:211], v[160:163], v[80:83]
	v_mfma_f32_16x16x32_bf16 v[76:79], v[216:219], v[160:163], v[76:79]
	v_mfma_f32_16x16x32_bf16 v[68:71], v[208:211], v[168:171], v[68:71]
	v_mfma_f32_16x16x32_bf16 v[64:67], v[216:219], v[168:171], v[64:67]
	v_mfma_f32_16x16x32_bf16 v[112:115], v[212:215], v[148:151], v[112:115]
	v_mfma_f32_16x16x32_bf16 v[108:111], v[220:223], v[148:151], v[108:111]
	v_mfma_f32_16x16x32_bf16 v[96:99], v[212:215], v[156:159], v[96:99]
	v_mfma_f32_16x16x32_bf16 v[92:95], v[220:223], v[156:159], v[92:95]
	v_mfma_f32_16x16x32_bf16 v[80:83], v[212:215], v[164:167], v[80:83]
	v_mfma_f32_16x16x32_bf16 v[76:79], v[220:223], v[164:167], v[76:79]
	v_mfma_f32_16x16x32_bf16 v[68:71], v[212:215], v[172:175], v[68:71]
	v_mfma_f32_16x16x32_bf16 v[64:67], v[220:223], v[172:175], v[64:67]
	s_setprio 0
	s_mov_b32 m0, s62
	v_lshl_add_u64 v[224:225], v[228:229], 0, s[30:31]
	s_barrier
	ds_read_b128 v[144:147], v197 offset:49152
	ds_read_b128 v[148:151], v197 offset:50176
	ds_read_b128 v[152:155], v197 offset:51200
	ds_read_b128 v[156:159], v197 offset:52224
	ds_read_b128 v[160:163], v197 offset:53248
	ds_read_b128 v[164:167], v197 offset:54272
	ds_read_b128 v[168:171], v197 offset:55296
	ds_read_b128 v[172:175], v197 offset:56320
	global_load_lds_dwordx4 v[224:225], off
	v_lshl_add_u64 v[224:225], v[242:243], 0, s[30:31]
	s_mov_b32 m0, s63
	s_nop 0
	global_load_lds_dwordx4 v[224:225], off
	s_barrier
; #define PG8_STAGE(bufoff, gbase, voff) do { _Pragma("unroll") for (int _i = 0; _i < 2; ++_i) \
;         __builtin_amdgcn_global_load_lds((const unsigned*)((const char*)(gbase) + (voff)[_i]), (LAS unsigned*)(lds + (bufoff) + ldsw + _i * 8192), 16, 0, 0); } while (0)
; #define PG8_MMA(ai, bj, At, Bt) do { __builtin_amdgcn_s_setprio(1); _Pragma("unroll") for (int m = 0; m < 4; ++m) _Pragma("unroll") for (int n = 0; n < 2; ++n) _Pragma("unroll") for (int k = 0; k < 2; ++k) \
;         acc[ai][bj][m][n] = __builtin_amdgcn_mfma_f32_16x16x32_bf16(Bt[n][k], At[m][k], acc[ai][bj][m][n], 0, 0, 0); __builtin_amdgcn_s_setprio(0); } while (0)
; #define PG8_WAIT_V(n) asm volatile("s_waitcnt vmcnt(" #n ")" ::: "memory")
; #define PG8_WAIT_L(n) asm volatile("s_waitcnt lgkmcnt(" #n ")" ::: "memory")
; #define PG8_BAR __builtin_amdgcn_s_barrier()
; #define PG8_SCHED __builtin_amdgcn_sched_barrier(0)
; template <class F>
; DI void gemm_phase(const int tid, LAS unsigned char* lds, const bf16_t* Ap, int lda, const bf16_t* Bp, int ldb, int M, int N, int K, int G, int c, bool direct, const F& E) {
;     ...
;             PG8_BAR; PG8_WAIT_L(0); PG8_MMA(1, 0, At, B0); PG8_BAR; PG8_SCHED;
;             PG8_STAGE(PG8_SB(1, 1), b3 + hsB, voffB);
;             PG8_WAIT_V(6); PG8_BAR; PG8_MMA(1, 1, At, B1); PG8_BAR;
;         }
;         if (E.kind == 7  ) E.fused(acc, cur.pm, cur.pn, wr, wc, fr, fq);
; DI void Epi::fused(const f32x4 (&acc)[2][2][4][2], int pm, int pn, int wr, int wc, int fr, int fq) const {
;     ...
;         const int ncol = pn * 256 + bj * 128 + wc * 32 + 8 * fq, j0 = (ncol >> 3) * 4;
;         const f32x4 wa0 = *(const f32x4*)(E.cf0 + j0), wa1 = *(const f32x4*)(E.cf0 + FF2 + j0), wa2 = *(const f32x4*)(E.cf0 + 2 * FF2 + j0);
;         const f32x4 wb0 = *(const f32x4*)(E.cf0 + FFH + j0), wb1 = *(const f32x4*)(E.cf0 + FF2 + FFH + j0), wb2 = *(const f32x4*)(E.cf0 + 2 * FF2 + FFH + j0);
;         const f32x4 ba = *(const f32x4*)(E.cf1 + j0), bb = *(const f32x4*)(E.cf1 + FFH + j0);
	s_waitcnt lgkmcnt(0)
	s_setprio 1
	s_waitcnt lgkmcnt(0)
	v_mfma_f32_16x16x32_bf16 v[60:63], v[128:131], v[144:147], v[60:63]
	v_mfma_f32_16x16x32_bf16 v[56:59], v[136:139], v[144:147], v[56:59]
	v_mfma_f32_16x16x32_bf16 v[52:55], v[128:131], v[152:155], v[52:55]
	v_mfma_f32_16x16x32_bf16 v[40:43], v[136:139], v[152:155], v[40:43]
	v_mfma_f32_16x16x32_bf16 v[36:39], v[128:131], v[160:163], v[36:39]
	v_mfma_f32_16x16x32_bf16 v[16:19], v[136:139], v[160:163], v[16:19]
	v_mfma_f32_16x16x32_bf16 v[12:15], v[128:131], v[168:171], v[12:15]
	v_mfma_f32_16x16x32_bf16 v[0:3], v[136:139], v[168:171], v[0:3]
	v_mfma_f32_16x16x32_bf16 v[60:63], v[132:135], v[148:151], v[60:63]
	v_mfma_f32_16x16x32_bf16 v[56:59], v[140:143], v[148:151], v[56:59]
	v_mfma_f32_16x16x32_bf16 v[52:55], v[132:135], v[156:159], v[52:55]
	v_mfma_f32_16x16x32_bf16 v[40:43], v[140:143], v[156:159], v[40:43]
	v_mfma_f32_16x16x32_bf16 v[36:39], v[132:135], v[164:167], v[36:39]
	v_mfma_f32_16x16x32_bf16 v[16:19], v[140:143], v[164:167], v[16:19]
	v_mfma_f32_16x16x32_bf16 v[12:15], v[132:135], v[172:175], v[12:15]
	v_mfma_f32_16x16x32_bf16 v[0:3], v[140:143], v[172:175], v[0:3]
	s_setprio 0
	s_barrier
	s_add_i32 s76, s76, s27
	v_lshl_add_u64 v[128:129], v[244:245], 0, s[30:31]
	s_mov_b32 m0, s76
	s_nop 0
	global_load_lds_dwordx4 v[128:129], off
	v_lshl_add_u64 v[128:129], v[246:247], 0, s[30:31]
	s_add_i32 m0, s76, 0x2000
	s_nop 0
	global_load_lds_dwordx4 v[128:129], off
	s_waitcnt vmcnt(6)
	s_barrier
	s_setprio 1
	v_mfma_f32_16x16x32_bf16 v[48:51], v[208:211], v[144:147], v[48:51]
	v_mfma_f32_16x16x32_bf16 v[44:47], v[216:219], v[144:147], v[44:47]
	v_mfma_f32_16x16x32_bf16 v[24:27], v[208:211], v[152:155], v[24:27]
	v_mfma_f32_16x16x32_bf16 v[20:23], v[216:219], v[152:155], v[20:23]
	v_mfma_f32_16x16x32_bf16 v[28:31], v[208:211], v[160:163], v[28:31]
	v_mfma_f32_16x16x32_bf16 v[32:35], v[216:219], v[160:163], v[32:35]
	v_mfma_f32_16x16x32_bf16 v[8:11], v[208:211], v[168:171], v[8:11]
	v_mfma_f32_16x16x32_bf16 v[4:7], v[216:219], v[168:171], v[4:7]
	v_mfma_f32_16x16x32_bf16 v[48:51], v[212:215], v[148:151], v[48:51]
	v_mfma_f32_16x16x32_bf16 v[44:47], v[220:223], v[148:151], v[44:47]
	v_mfma_f32_16x16x32_bf16 v[24:27], v[212:215], v[156:159], v[24:27]
	v_mfma_f32_16x16x32_bf16 v[20:23], v[220:223], v[156:159], v[20:23]
	v_mfma_f32_16x16x32_bf16 v[28:31], v[212:215], v[164:167], v[28:31]
	v_mfma_f32_16x16x32_bf16 v[32:35], v[220:223], v[164:167], v[32:35]
	v_mfma_f32_16x16x32_bf16 v[8:11], v[212:215], v[172:175], v[8:11]
	v_mfma_f32_16x16x32_bf16 v[4:7], v[220:223], v[172:175], v[4:7]
	s_setprio 0
	s_add_u32 s74, s74, 0x100
	s_addc_u32 s75, s75, 0
	s_add_u32 s71, s71, 0x100
	s_addc_u32 s80, s80, 0
	s_cmp_ge_u32 s81, s26
	s_mov_b32 s76, s81
	s_barrier
	s_cbranch_scc0 .LBB0_657
	s_mov_b64 s[76:77], -1
	s_mov_b64 s[74:75], 0
	s_cmp_lt_i32 s92, 3
	s_mov_b64 s[78:79], 0
	s_cbranch_scc1 .LBB0_688
	s_cmp_gt_i32 s92, 6
	s_mov_b64 s[78:79], -1
	s_cbranch_scc0 .LBB0_685
	v_lshl_or_b32 v240, s70, 8, v194
	v_mov_b32_e32 v241, 0
	s_lshl_b32 s71, s36, 8
	v_readlane_b32 s76, v255, 16
	s_nop 3
	s_add_i32 s71, s71, s76
	v_or_b32_e32 v199, s71, v188
	v_lshlrev_b32_e32 v238, 1, v240
	v_mov_b32_e32 v239, 0
	v_lshl_add_u64 v[136:137], s[22:23], 0, v[238:239]
	global_load_dwordx4 v[136:139], v[136:137], off
	v_readlane_b32 s76, v254, 54
	v_readlane_b32 s77, v254, 55
	s_nop 1
	v_lshl_add_u64 v[140:141], s[76:77], 0, v[238:239]
	global_load_dwordx4 v[140:143], v[140:141], off
	v_readlane_b32 s76, v254, 56
	v_readlane_b32 s77, v254, 57
	s_nop 1
	v_lshl_add_u64 v[152:153], s[76:77], 0, v[238:239]
	global_load_dwordx4 v[152:155], v[152:153], off
	v_readlane_b32 s76, v255, 4
	v_readlane_b32 s77, v255, 5
	s_nop 1
	v_lshl_add_u64 v[128:129], s[76:77], 0, v[238:239]
	global_load_dwordx4 v[128:131], v[128:129], off
	v_readlane_b32 s76, v255, 6
	v_readlane_b32 s77, v255, 7
	s_nop 1
	v_lshl_add_u64 v[132:133], s[76:77], 0, v[238:239]
	global_load_dwordx4 v[132:135], v[132:133], off
	v_readlane_b32 s76, v255, 8
	v_readlane_b32 s77, v255, 9
	s_nop 1
	v_lshl_add_u64 v[144:145], s[76:77], 0, v[238:239]
	global_load_dwordx4 v[144:147], v[144:145], off
	v_readlane_b32 s76, v254, 49
	v_readlane_b32 s77, v254, 50
	s_nop 1
	v_lshl_add_u64 v[156:157], s[76:77], 0, v[238:239]
	global_load_dwordx4 v[156:159], v[156:157], off
	v_lshl_add_u64 v[148:149], s[72:73], 0, v[238:239]
	global_load_dwordx4 v[148:151], v[148:149], off
	v_mov_b32_e32 v228, v199
	v_mov_b64_e32 v[224:225], s[12:13]
	s_movk_i32 s80, 0x1600
	v_mad_i64_i32 v[224:225], s[78:79], v228, s80, v[224:225]
	v_mov_b32_e32 v228, v240
	v_mov_b32_e32 v229, 0
	v_lshl_add_u64 v[224:225], v[228:229], 0, v[224:225]
	s_waitcnt vmcnt(0)
; DI float silu_fast(float x) { return x * __builtin_amdgcn_rcpf(1.f + __expf(-x)); }
; template <int CTRL> DI float dppf(float v) { return __builtin_bit_cast(float, __builtin_amdgcn_update_dpp(0, __builtin_bit_cast(int, v), CTRL, 0xf, 0xf, true)); }
; DI void Epi::fused(const f32x4 (&acc)[2][2][4][2], int pm, int pn, int wr, int wc, int fr, int fq) const {
;     ...
;             for (int m = 0; m < 4; ++m) {
;                 const f32x4 ca = acc[ai][bj][m][0], cb = acc[ai][bj][m][1];
;                 const int row = pm * 256 + ai * 128 + wr * 64 + m * 16 + fr;
;                 float o[4];
; #pragma unroll
;                 for (int e = 0; e < 4; ++e) {
;                     const float a1 = dppf<0x111>(ca[e]) + dppf<0x10F>(pa[e]), a2 = dppf<0x112>(ca[e]) + dppf<0x10E>(pa[e]);
;                     const float b1 = dppf<0x111>(cb[e]) + dppf<0x10F>(pb[e]), b2 = dppf<0x112>(cb[e]) + dppf<0x10E>(pb[e]);
;                     const float ya = fmaf(wa0[e], a2, fmaf(wa1[e], a1, fmaf(wa2[e], ca[e], ba[e])));
;                     const float yb = fmaf(wb0[e], b2, fmaf(wb1[e], b1, fmaf(wb2[e], cb[e], bb[e])));
;                     o[e] = silu_fast(ya) * yb; }
;                 if (m > 0 || fr >= 2) { u32x2 w; w.x = pk2(o[0], o[1]); w.y = pk2(o[2], o[3]); *(u32x2*)(E.d0 + (size_t)row * FFH + j0) = w; }
;                 if ((m == 0 && fr < 2) || (m == 3 && fr >= 14)) { float* hb = E.f0 + ((size_t)(row >> 6) * 4 + (m == 0 ? fr : fr - 12)) * FF2 + ncol; *(f32x4*)hb = ca; *(f32x4*)(hb + 4) = cb; }
	v_fma_f32 v160, v152, v124, v156
	v_fma_f32 v161, v153, v125, v157
	v_fma_f32 v162, v154, v126, v158
	v_fma_f32 v163, v155, v127, v159
	v_fma_f32 v164, v144, v120, v148
	v_fma_f32 v165, v145, v121, v149
	v_fma_f32 v166, v146, v122, v150
	v_fma_f32 v167, v147, v123, v151
	v_fmac_f32_dpp v160, v124, v140 row_shr:1 row_mask:0xf bank_mask:0xf
	v_fmac_f32_dpp v161, v125, v141 row_shr:1 row_mask:0xf bank_mask:0xf
	v_fmac_f32_dpp v162, v126, v142 row_shr:1 row_mask:0xf bank_mask:0xf
	v_fmac_f32_dpp v163, v127, v143 row_shr:1 row_mask:0xf bank_mask:0xf
	v_fmac_f32_dpp v164, v120, v132 row_shr:1 row_mask:0xf bank_mask:0xf
	v_fmac_f32_dpp v165, v121, v133 row_shr:1 row_mask:0xf bank_mask:0xf
	v_fmac_f32_dpp v166, v122, v134 row_shr:1 row_mask:0xf bank_mask:0xf
	v_fmac_f32_dpp v167, v123, v135 row_shr:1 row_mask:0xf bank_mask:0xf
	v_fmac_f32_dpp v160, v124, v136 row_shr:2 row_mask:0xf bank_mask:0xf
	v_fmac_f32_dpp v161, v125, v137 row_shr:2 row_mask:0xf bank_mask:0xf
	v_fmac_f32_dpp v162, v126, v138 row_shr:2 row_mask:0xf bank_mask:0xf
	v_fmac_f32_dpp v163, v127, v139 row_shr:2 row_mask:0xf bank_mask:0xf
	v_fmac_f32_dpp v164, v120, v128 row_shr:2 row_mask:0xf bank_mask:0xf
	v_fmac_f32_dpp v165, v121, v129 row_shr:2 row_mask:0xf bank_mask:0xf
	v_fmac_f32_dpp v166, v122, v130 row_shr:2 row_mask:0xf bank_mask:0xf
	v_fmac_f32_dpp v167, v123, v131 row_shr:2 row_mask:0xf bank_mask:0xf
	v_mul_f32_e32 v168, 0xbfb8aa3b, v160
	v_mul_f32_e32 v169, 0xbfb8aa3b, v161
	v_mul_f32_e32 v170, 0xbfb8aa3b, v162
	v_mul_f32_e32 v171, 0xbfb8aa3b, v163
	v_exp_f32_e32 v168, v168
	v_exp_f32_e32 v169, v169
	v_exp_f32_e32 v170, v170
	v_exp_f32_e32 v171, v171
	v_add_f32_e32 v168, 1.0, v168
	v_add_f32_e32 v169, 1.0, v169
	v_add_f32_e32 v170, 1.0, v170
	v_add_f32_e32 v171, 1.0, v171
	v_rcp_f32_e32 v168, v168
	v_rcp_f32_e32 v169, v169
	v_rcp_f32_e32 v170, v170
	v_rcp_f32_e32 v171, v171
	v_mov_b64_e32 v[174:175], v[224:225]
	v_mul_f32_e32 v160, v160, v168
	v_mul_f32_e32 v161, v161, v169
	v_mul_f32_e32 v162, v162, v170
	v_mul_f32_e32 v163, v163, v171
	v_mul_f32_e32 v160, v164, v160
	v_mul_f32_e32 v161, v165, v161
	v_mul_f32_e32 v162, v166, v162
	v_mul_f32_e32 v163, v167, v163
	v_cvt_pk_bf16_f32 v172, v160, v161
	v_cvt_pk_bf16_f32 v173, v162, v163
	s_and_saveexec_b64 s[76:77], s[38:39]
	global_store_dwordx2 v[174:175], v[172:173], off
	s_or_b64 exec, exec, s[76:77]
	s_ashr_i32 s80, s71, 6
	s_lshl_b32 s80, s80, 2
	v_add_u32_e32 v226, s80, v188
	v_mov_b64_e32 v[174:175], s[8:9]
	s_movk_i32 s80, 0x5800
	v_mad_i64_i32 v[174:175], s[78:79], v226, s80, v[174:175]
	v_lshl_add_u64 v[174:175], v[228:229], 2, v[174:175]
	s_and_saveexec_b64 s[76:77], s[40:41]
	global_store_dwordx4 v[174:175], v[124:127], off
	global_store_dwordx4 v[174:175], v[120:123], off offset:16
	s_or_b64 exec, exec, s[76:77]
	v_fma_f32 v208, v152, v116, v156
	v_fma_f32 v209, v153, v117, v157
	v_fma_f32 v210, v154, v118, v158
	v_fma_f32 v211, v155, v119, v159
	v_fma_f32 v212, v144, v104, v148
	v_fma_f32 v213, v145, v105, v149
	v_fma_f32 v214, v146, v106, v150
	v_fma_f32 v215, v147, v107, v151
	v_fmac_f32_dpp v208, v116, v140 row_shr:1 row_mask:0xf bank_mask:0xf
	v_fmac_f32_dpp v209, v117, v141 row_shr:1 row_mask:0xf bank_mask:0xf
	v_fmac_f32_dpp v210, v118, v142 row_shr:1 row_mask:0xf bank_mask:0xf
	v_fmac_f32_dpp v211, v119, v143 row_shr:1 row_mask:0xf bank_mask:0xf
	v_fmac_f32_dpp v212, v104, v132 row_shr:1 row_mask:0xf bank_mask:0xf
	v_fmac_f32_dpp v213, v105, v133 row_shr:1 row_mask:0xf bank_mask:0xf
	v_fmac_f32_dpp v214, v106, v134 row_shr:1 row_mask:0xf bank_mask:0xf
	v_fmac_f32_dpp v215, v107, v135 row_shr:1 row_mask:0xf bank_mask:0xf
	v_fmac_f32_dpp v208, v124, v140 row_shl:15 row_mask:0xf bank_mask:0xf
	v_fmac_f32_dpp v209, v125, v141 row_shl:15 row_mask:0xf bank_mask:0xf
	v_fmac_f32_dpp v210, v126, v142 row_shl:15 row_mask:0xf bank_mask:0xf
	v_fmac_f32_dpp v211, v127, v143 row_shl:15 row_mask:0xf bank_mask:0xf
	v_fmac_f32_dpp v212, v120, v132 row_shl:15 row_mask:0xf bank_mask:0xf
	v_fmac_f32_dpp v213, v121, v133 row_shl:15 row_mask:0xf bank_mask:0xf
	v_fmac_f32_dpp v214, v122, v134 row_shl:15 row_mask:0xf bank_mask:0xf
	v_fmac_f32_dpp v215, v123, v135 row_shl:15 row_mask:0xf bank_mask:0xf
	v_fmac_f32_dpp v208, v116, v136 row_shr:2 row_mask:0xf bank_mask:0xf
	v_fmac_f32_dpp v209, v117, v137 row_shr:2 row_mask:0xf bank_mask:0xf
	v_fmac_f32_dpp v210, v118, v138 row_shr:2 row_mask:0xf bank_mask:0xf
	v_fmac_f32_dpp v211, v119, v139 row_shr:2 row_mask:0xf bank_mask:0xf
	v_fmac_f32_dpp v212, v104, v128 row_shr:2 row_mask:0xf bank_mask:0xf
	v_fmac_f32_dpp v213, v105, v129 row_shr:2 row_mask:0xf bank_mask:0xf
	v_fmac_f32_dpp v214, v106, v130 row_shr:2 row_mask:0xf bank_mask:0xf
	v_fmac_f32_dpp v215, v107, v131 row_shr:2 row_mask:0xf bank_mask:0xf
	v_fmac_f32_dpp v208, v124, v136 row_shl:14 row_mask:0xf bank_mask:0xf
	v_fmac_f32_dpp v209, v125, v137 row_shl:14 row_mask:0xf bank_mask:0xf
	v_fmac_f32_dpp v210, v126, v138 row_shl:14 row_mask:0xf bank_mask:0xf
	v_fmac_f32_dpp v211, v127, v139 row_shl:14 row_mask:0xf bank_mask:0xf
	v_fmac_f32_dpp v212, v120, v128 row_shl:14 row_mask:0xf bank_mask:0xf
	v_fmac_f32_dpp v213, v121, v129 row_shl:14 row_mask:0xf bank_mask:0xf
	v_fmac_f32_dpp v214, v122, v130 row_shl:14 row_mask:0xf bank_mask:0xf
	v_fmac_f32_dpp v215, v123, v131 row_shl:14 row_mask:0xf bank_mask:0xf
	v_mul_f32_e32 v216, 0xbfb8aa3b, v208
	v_mul_f32_e32 v217, 0xbfb8aa3b, v209
	v_mul_f32_e32 v218, 0xbfb8aa3b, v210
	v_mul_f32_e32 v219, 0xbfb8aa3b, v211
	v_exp_f32_e32 v216, v216
	v_exp_f32_e32 v217, v217
	v_exp_f32_e32 v218, v218
	v_exp_f32_e32 v219, v219
	v_add_f32_e32 v216, 1.0, v216
	v_add_f32_e32 v217, 1.0, v217
; DI float silu_fast(float x) { return x * __builtin_amdgcn_rcpf(1.f + __expf(-x)); }
; template <int CTRL> DI float dppf(float v) { return __builtin_bit_cast(float, __builtin_amdgcn_update_dpp(0, __builtin_bit_cast(int, v), CTRL, 0xf, 0xf, true)); }
; DI void Epi::fused(const f32x4 (&acc)[2][2][4][2], int pm, int pn, int wr, int wc, int fr, int fq) const {
;     ...
;             for (int m = 0; m < 4; ++m) {
;                 const f32x4 ca = acc[ai][bj][m][0], cb = acc[ai][bj][m][1];
;                 const int row = pm * 256 + ai * 128 + wr * 64 + m * 16 + fr;
;                 float o[4];
; #pragma unroll
;                 for (int e = 0; e < 4; ++e) {
;                     const float a1 = dppf<0x111>(ca[e]) + dppf<0x10F>(pa[e]), a2 = dppf<0x112>(ca[e]) + dppf<0x10E>(pa[e]);
;                     const float b1 = dppf<0x111>(cb[e]) + dppf<0x10F>(pb[e]), b2 = dppf<0x112>(cb[e]) + dppf<0x10E>(pb[e]);
;                     const float ya = fmaf(wa0[e], a2, fmaf(wa1[e], a1, fmaf(wa2[e], ca[e], ba[e])));
;                     const float yb = fmaf(wb0[e], b2, fmaf(wb1[e], b1, fmaf(wb2[e], cb[e], bb[e])));
;                     o[e] = silu_fast(ya) * yb; }
;                 if (m > 0 || fr >= 2) { u32x2 w; w.x = pk2(o[0], o[1]); w.y = pk2(o[2], o[3]); *(u32x2*)(E.d0 + (size_t)row * FFH + j0) = w; }
	v_add_f32_e32 v218, 1.0, v218
	v_add_f32_e32 v219, 1.0, v219
	v_rcp_f32_e32 v216, v216
	v_rcp_f32_e32 v217, v217
	v_rcp_f32_e32 v218, v218
	v_rcp_f32_e32 v219, v219
	s_mov_b32 s80, 0x16000
	s_mov_b32 s81, 0
	v_lshl_add_u64 v[222:223], v[224:225], 0, s[80:81]
	v_mul_f32_e32 v208, v208, v216
	v_mul_f32_e32 v209, v209, v217
	v_mul_f32_e32 v210, v210, v218
	v_mul_f32_e32 v211, v211, v219
	v_mul_f32_e32 v208, v212, v208
	v_mul_f32_e32 v209, v213, v209
	v_mul_f32_e32 v210, v214, v210
	v_mul_f32_e32 v211, v215, v211
	v_cvt_pk_bf16_f32 v220, v208, v209
	v_cvt_pk_bf16_f32 v221, v210, v211
	global_store_dwordx2 v[222:223], v[220:221], off
	v_fma_f32 v160, v152, v100, v156
	v_fma_f32 v161, v153, v101, v157
	v_fma_f32 v162, v154, v102, v158
	v_fma_f32 v163, v155, v103, v159
	v_fma_f32 v164, v144, v88, v148
	v_fma_f32 v165, v145, v89, v149
	v_fma_f32 v166, v146, v90, v150
	v_fma_f32 v167, v147, v91, v151
	v_fmac_f32_dpp v160, v100, v140 row_shr:1 row_mask:0xf bank_mask:0xf
	v_fmac_f32_dpp v161, v101, v141 row_shr:1 row_mask:0xf bank_mask:0xf
	v_fmac_f32_dpp v162, v102, v142 row_shr:1 row_mask:0xf bank_mask:0xf
	v_fmac_f32_dpp v163, v103, v143 row_shr:1 row_mask:0xf bank_mask:0xf
	v_fmac_f32_dpp v164, v88, v132 row_shr:1 row_mask:0xf bank_mask:0xf
	v_fmac_f32_dpp v165, v89, v133 row_shr:1 row_mask:0xf bank_mask:0xf
	v_fmac_f32_dpp v166, v90, v134 row_shr:1 row_mask:0xf bank_mask:0xf
	v_fmac_f32_dpp v167, v91, v135 row_shr:1 row_mask:0xf bank_mask:0xf
	v_fmac_f32_dpp v160, v116, v140 row_shl:15 row_mask:0xf bank_mask:0xf
	v_fmac_f32_dpp v161, v117, v141 row_shl:15 row_mask:0xf bank_mask:0xf
	v_fmac_f32_dpp v162, v118, v142 row_shl:15 row_mask:0xf bank_mask:0xf
	v_fmac_f32_dpp v163, v119, v143 row_shl:15 row_mask:0xf bank_mask:0xf
	v_fmac_f32_dpp v164, v104, v132 row_shl:15 row_mask:0xf bank_mask:0xf
	v_fmac_f32_dpp v165, v105, v133 row_shl:15 row_mask:0xf bank_mask:0xf
	v_fmac_f32_dpp v166, v106, v134 row_shl:15 row_mask:0xf bank_mask:0xf
	v_fmac_f32_dpp v167, v107, v135 row_shl:15 row_mask:0xf bank_mask:0xf
	v_fmac_f32_dpp v160, v100, v136 row_shr:2 row_mask:0xf bank_mask:0xf
	v_fmac_f32_dpp v161, v101, v137 row_shr:2 row_mask:0xf bank_mask:0xf
	v_fmac_f32_dpp v162, v102, v138 row_shr:2 row_mask:0xf bank_mask:0xf
	v_fmac_f32_dpp v163, v103, v139 row_shr:2 row_mask:0xf bank_mask:0xf
	v_fmac_f32_dpp v164, v88, v128 row_shr:2 row_mask:0xf bank_mask:0xf
	v_fmac_f32_dpp v165, v89, v129 row_shr:2 row_mask:0xf bank_mask:0xf
	v_fmac_f32_dpp v166, v90, v130 row_shr:2 row_mask:0xf bank_mask:0xf
	v_fmac_f32_dpp v167, v91, v131 row_shr:2 row_mask:0xf bank_mask:0xf
	v_fmac_f32_dpp v160, v116, v136 row_shl:14 row_mask:0xf bank_mask:0xf
	v_fmac_f32_dpp v161, v117, v137 row_shl:14 row_mask:0xf bank_mask:0xf
	v_fmac_f32_dpp v162, v118, v138 row_shl:14 row_mask:0xf bank_mask:0xf
	v_fmac_f32_dpp v163, v119, v139 row_shl:14 row_mask:0xf bank_mask:0xf
	v_fmac_f32_dpp v164, v104, v128 row_shl:14 row_mask:0xf bank_mask:0xf
	v_fmac_f32_dpp v165, v105, v129 row_shl:14 row_mask:0xf bank_mask:0xf
	v_fmac_f32_dpp v166, v106, v130 row_shl:14 row_mask:0xf bank_mask:0xf
	v_fmac_f32_dpp v167, v107, v131 row_shl:14 row_mask:0xf bank_mask:0xf
	v_mul_f32_e32 v168, 0xbfb8aa3b, v160
	v_mul_f32_e32 v169, 0xbfb8aa3b, v161
	v_mul_f32_e32 v170, 0xbfb8aa3b, v162
	v_mul_f32_e32 v171, 0xbfb8aa3b, v163
	v_exp_f32_e32 v168, v168
	v_exp_f32_e32 v169, v169
	v_exp_f32_e32 v170, v170
	v_exp_f32_e32 v171, v171
	v_add_f32_e32 v168, 1.0, v168
	v_add_f32_e32 v169, 1.0, v169
	v_add_f32_e32 v170, 1.0, v170
	v_add_f32_e32 v171, 1.0, v171
	v_rcp_f32_e32 v168, v168
	v_rcp_f32_e32 v169, v169
	v_rcp_f32_e32 v170, v170
	v_rcp_f32_e32 v171, v171
	s_mov_b32 s80, 0x2c000
	s_mov_b32 s81, 0
	v_lshl_add_u64 v[174:175], v[224:225], 0, s[80:81]
	v_mul_f32_e32 v160, v160, v168
	v_mul_f32_e32 v161, v161, v169
	v_mul_f32_e32 v162, v162, v170
	v_mul_f32_e32 v163, v163, v171
	v_mul_f32_e32 v160, v164, v160
	v_mul_f32_e32 v161, v165, v161
	v_mul_f32_e32 v162, v166, v162
	v_mul_f32_e32 v163, v167, v163
	v_cvt_pk_bf16_f32 v172, v160, v161
	v_cvt_pk_bf16_f32 v173, v162, v163
	global_store_dwordx2 v[174:175], v[172:173], off
	v_fma_f32 v208, v152, v84, v156
	v_fma_f32 v209, v153, v85, v157
	v_fma_f32 v210, v154, v86, v158
	v_fma_f32 v211, v155, v87, v159
	v_fma_f32 v212, v144, v72, v148
	v_fma_f32 v213, v145, v73, v149
	v_fma_f32 v214, v146, v74, v150
	v_fma_f32 v215, v147, v75, v151
	v_fmac_f32_dpp v208, v84, v140 row_shr:1 row_mask:0xf bank_mask:0xf
	v_fmac_f32_dpp v209, v85, v141 row_shr:1 row_mask:0xf bank_mask:0xf
	v_fmac_f32_dpp v210, v86, v142 row_shr:1 row_mask:0xf bank_mask:0xf
	v_fmac_f32_dpp v211, v87, v143 row_shr:1 row_mask:0xf bank_mask:0xf
	v_fmac_f32_dpp v212, v72, v132 row_shr:1 row_mask:0xf bank_mask:0xf
	v_fmac_f32_dpp v213, v73, v133 row_shr:1 row_mask:0xf bank_mask:0xf
	v_fmac_f32_dpp v214, v74, v134 row_shr:1 row_mask:0xf bank_mask:0xf
	v_fmac_f32_dpp v215, v75, v135 row_shr:1 row_mask:0xf bank_mask:0xf
	v_fmac_f32_dpp v208, v100, v140 row_shl:15 row_mask:0xf bank_mask:0xf
	v_fmac_f32_dpp v209, v101, v141 row_shl:15 row_mask:0xf bank_mask:0xf
	v_fmac_f32_dpp v210, v102, v142 row_shl:15 row_mask:0xf bank_mask:0xf
	v_fmac_f32_dpp v211, v103, v143 row_shl:15 row_mask:0xf bank_mask:0xf
	v_fmac_f32_dpp v212, v88, v132 row_shl:15 row_mask:0xf bank_mask:0xf
	v_fmac_f32_dpp v213, v89, v133 row_shl:15 row_mask:0xf bank_mask:0xf
	v_fmac_f32_dpp v214, v90, v134 row_shl:15 row_mask:0xf bank_mask:0xf
	v_fmac_f32_dpp v215, v91, v135 row_shl:15 row_mask:0xf bank_mask:0xf
	v_fmac_f32_dpp v208, v84, v136 row_shr:2 row_mask:0xf bank_mask:0xf
	v_fmac_f32_dpp v209, v85, v137 row_shr:2 row_mask:0xf bank_mask:0xf
; DI float silu_fast(float x) { return x * __builtin_amdgcn_rcpf(1.f + __expf(-x)); }
; template <int CTRL> DI float dppf(float v) { return __builtin_bit_cast(float, __builtin_amdgcn_update_dpp(0, __builtin_bit_cast(int, v), CTRL, 0xf, 0xf, true)); }
; DI void Epi::fused(const f32x4 (&acc)[2][2][4][2], int pm, int pn, int wr, int wc, int fr, int fq) const {
;     ...
;         const int ncol = pn * 256 + bj * 128 + wc * 32 + 8 * fq, j0 = (ncol >> 3) * 4;
;         const f32x4 wa0 = *(const f32x4*)(E.cf0 + j0), wa1 = *(const f32x4*)(E.cf0 + FF2 + j0), wa2 = *(const f32x4*)(E.cf0 + 2 * FF2 + j0);
;         const f32x4 wb0 = *(const f32x4*)(E.cf0 + FFH + j0), wb1 = *(const f32x4*)(E.cf0 + FF2 + FFH + j0), wb2 = *(const f32x4*)(E.cf0 + 2 * FF2 + FFH + j0);
;         const f32x4 ba = *(const f32x4*)(E.cf1 + j0), bb = *(const f32x4*)(E.cf1 + FFH + j0);
; #pragma unroll
;         for (int ai = 0; ai < 2; ++ai) {
;             f32x4 pa = (f32x4){0.f, 0.f, 0.f, 0.f}, pb = pa;
; #pragma unroll
;             for (int m = 0; m < 4; ++m) {
;                 const f32x4 ca = acc[ai][bj][m][0], cb = acc[ai][bj][m][1];
;                 const int row = pm * 256 + ai * 128 + wr * 64 + m * 16 + fr;
;                 float o[4];
; #pragma unroll
;                 for (int e = 0; e < 4; ++e) {
;                     const float a1 = dppf<0x111>(ca[e]) + dppf<0x10F>(pa[e]), a2 = dppf<0x112>(ca[e]) + dppf<0x10E>(pa[e]);
;                     const float b1 = dppf<0x111>(cb[e]) + dppf<0x10F>(pb[e]), b2 = dppf<0x112>(cb[e]) + dppf<0x10E>(pb[e]);
;                     const float ya = fmaf(wa0[e], a2, fmaf(wa1[e], a1, fmaf(wa2[e], ca[e], ba[e])));
;                     const float yb = fmaf(wb0[e], b2, fmaf(wb1[e], b1, fmaf(wb2[e], cb[e], bb[e])));
;                     o[e] = silu_fast(ya) * yb; }
;                 if (m > 0 || fr >= 2) { u32x2 w; w.x = pk2(o[0], o[1]); w.y = pk2(o[2], o[3]); *(u32x2*)(E.d0 + (size_t)row * FFH + j0) = w; }
;                 if ((m == 0 && fr < 2) || (m == 3 && fr >= 14)) { float* hb = E.f0 + ((size_t)(row >> 6) * 4 + (m == 0 ? fr : fr - 12)) * FF2 + ncol; *(f32x4*)hb = ca; *(f32x4*)(hb + 4) = cb; }
	v_fmac_f32_dpp v210, v86, v138 row_shr:2 row_mask:0xf bank_mask:0xf
	v_fmac_f32_dpp v211, v87, v139 row_shr:2 row_mask:0xf bank_mask:0xf
	v_fmac_f32_dpp v212, v72, v128 row_shr:2 row_mask:0xf bank_mask:0xf
	v_fmac_f32_dpp v213, v73, v129 row_shr:2 row_mask:0xf bank_mask:0xf
	v_fmac_f32_dpp v214, v74, v130 row_shr:2 row_mask:0xf bank_mask:0xf
	v_fmac_f32_dpp v215, v75, v131 row_shr:2 row_mask:0xf bank_mask:0xf
	v_fmac_f32_dpp v208, v100, v136 row_shl:14 row_mask:0xf bank_mask:0xf
	v_fmac_f32_dpp v209, v101, v137 row_shl:14 row_mask:0xf bank_mask:0xf
	v_fmac_f32_dpp v210, v102, v138 row_shl:14 row_mask:0xf bank_mask:0xf
	v_fmac_f32_dpp v211, v103, v139 row_shl:14 row_mask:0xf bank_mask:0xf
	v_fmac_f32_dpp v212, v88, v128 row_shl:14 row_mask:0xf bank_mask:0xf
	v_fmac_f32_dpp v213, v89, v129 row_shl:14 row_mask:0xf bank_mask:0xf
	v_fmac_f32_dpp v214, v90, v130 row_shl:14 row_mask:0xf bank_mask:0xf
	v_fmac_f32_dpp v215, v91, v131 row_shl:14 row_mask:0xf bank_mask:0xf
	v_mul_f32_e32 v216, 0xbfb8aa3b, v208
	v_mul_f32_e32 v217, 0xbfb8aa3b, v209
	v_mul_f32_e32 v218, 0xbfb8aa3b, v210
	v_mul_f32_e32 v219, 0xbfb8aa3b, v211
	v_exp_f32_e32 v216, v216
	v_exp_f32_e32 v217, v217
	v_exp_f32_e32 v218, v218
	v_exp_f32_e32 v219, v219
	v_add_f32_e32 v216, 1.0, v216
	v_add_f32_e32 v217, 1.0, v217
	v_add_f32_e32 v218, 1.0, v218
	v_add_f32_e32 v219, 1.0, v219
	v_rcp_f32_e32 v216, v216
	v_rcp_f32_e32 v217, v217
	v_rcp_f32_e32 v218, v218
	v_rcp_f32_e32 v219, v219
	s_mov_b32 s80, 0x42000
	s_mov_b32 s81, 0
	v_lshl_add_u64 v[222:223], v[224:225], 0, s[80:81]
	v_mul_f32_e32 v208, v208, v216
	v_mul_f32_e32 v209, v209, v217
	v_mul_f32_e32 v210, v210, v218
	v_mul_f32_e32 v211, v211, v219
	v_mul_f32_e32 v208, v212, v208
	v_mul_f32_e32 v209, v213, v209
	v_mul_f32_e32 v210, v214, v210
	v_mul_f32_e32 v211, v215, v211
	v_cvt_pk_bf16_f32 v220, v208, v209
	v_cvt_pk_bf16_f32 v221, v210, v211
	global_store_dwordx2 v[222:223], v[220:221], off
	s_ashr_i32 s80, s71, 6
	s_lshl_b32 s80, s80, 2
	v_add_u32_e32 v226, s80, v190
	v_mov_b64_e32 v[222:223], s[8:9]
	s_movk_i32 s80, 0x5800
	v_mad_i64_i32 v[222:223], s[78:79], v226, s80, v[222:223]
	v_lshl_add_u64 v[222:223], v[228:229], 2, v[222:223]
	s_and_saveexec_b64 s[76:77], s[42:43]
	global_store_dwordx4 v[222:223], v[84:87], off
	global_store_dwordx4 v[222:223], v[72:75], off offset:16
	s_or_b64 exec, exec, s[76:77]
	v_add_u32_e32 v238, 0x80, v240
	v_lshlrev_b32_e32 v238, 1, v238
	v_mov_b32_e32 v239, 0
	v_lshl_add_u64 v[84:85], s[22:23], 0, v[238:239]
	global_load_dwordx4 v[84:87], v[84:85], off
	v_readlane_b32 s76, v254, 54
	v_readlane_b32 s77, v254, 55
	s_nop 1
	v_lshl_add_u64 v[88:89], s[76:77], 0, v[238:239]
	global_load_dwordx4 v[88:91], v[88:89], off
	v_readlane_b32 s76, v254, 56
	v_readlane_b32 s77, v254, 57
	s_nop 1
	v_lshl_add_u64 v[100:101], s[76:77], 0, v[238:239]
	global_load_dwordx4 v[100:103], v[100:101], off
	v_readlane_b32 s76, v255, 4
	v_readlane_b32 s77, v255, 5
	s_nop 1
	v_lshl_add_u64 v[104:105], s[76:77], 0, v[238:239]
	global_load_dwordx4 v[104:107], v[104:105], off
	v_readlane_b32 s76, v255, 6
	v_readlane_b32 s77, v255, 7
	s_nop 1
	v_lshl_add_u64 v[116:117], s[76:77], 0, v[238:239]
	global_load_dwordx4 v[116:119], v[116:117], off
	v_readlane_b32 s76, v255, 8
	v_readlane_b32 s77, v255, 9
	s_nop 1
	v_lshl_add_u64 v[120:121], s[76:77], 0, v[238:239]
	global_load_dwordx4 v[120:123], v[120:121], off
	v_readlane_b32 s76, v254, 49
	v_readlane_b32 s77, v254, 50
	s_nop 1
	v_lshl_add_u64 v[124:125], s[76:77], 0, v[238:239]
	global_load_dwordx4 v[124:127], v[124:125], off
	v_lshl_add_u64 v[72:73], s[72:73], 0, v[238:239]
	global_load_dwordx4 v[72:75], v[72:73], off
	v_add_u32_e32 v228, 128, v199
	v_mov_b64_e32 v[224:225], s[12:13]
	s_movk_i32 s80, 0x1600
	v_mad_i64_i32 v[224:225], s[78:79], v228, s80, v[224:225]
	v_mov_b32_e32 v228, v240
	v_mov_b32_e32 v229, 0
	v_lshl_add_u64 v[224:225], v[228:229], 0, v[224:225]
	v_fma_f32 v160, v152, v60, v156
	v_fma_f32 v161, v153, v61, v157
	v_fma_f32 v162, v154, v62, v158
	v_fma_f32 v163, v155, v63, v159
	v_fma_f32 v164, v144, v56, v148
	v_fma_f32 v165, v145, v57, v149
	v_fma_f32 v166, v146, v58, v150
	v_fma_f32 v167, v147, v59, v151
	v_fmac_f32_dpp v160, v60, v140 row_shr:1 row_mask:0xf bank_mask:0xf
	v_fmac_f32_dpp v161, v61, v141 row_shr:1 row_mask:0xf bank_mask:0xf
	v_fmac_f32_dpp v162, v62, v142 row_shr:1 row_mask:0xf bank_mask:0xf
	v_fmac_f32_dpp v163, v63, v143 row_shr:1 row_mask:0xf bank_mask:0xf
	v_fmac_f32_dpp v164, v56, v132 row_shr:1 row_mask:0xf bank_mask:0xf
	v_fmac_f32_dpp v165, v57, v133 row_shr:1 row_mask:0xf bank_mask:0xf
	v_fmac_f32_dpp v166, v58, v134 row_shr:1 row_mask:0xf bank_mask:0xf
	v_fmac_f32_dpp v167, v59, v135 row_shr:1 row_mask:0xf bank_mask:0xf
	v_fmac_f32_dpp v160, v60, v136 row_shr:2 row_mask:0xf bank_mask:0xf
	v_fmac_f32_dpp v161, v61, v137 row_shr:2 row_mask:0xf bank_mask:0xf
	v_fmac_f32_dpp v162, v62, v138 row_shr:2 row_mask:0xf bank_mask:0xf
	v_fmac_f32_dpp v163, v63, v139 row_shr:2 row_mask:0xf bank_mask:0xf
	v_fmac_f32_dpp v164, v56, v128 row_shr:2 row_mask:0xf bank_mask:0xf
	v_fmac_f32_dpp v165, v57, v129 row_shr:2 row_mask:0xf bank_mask:0xf
	v_fmac_f32_dpp v166, v58, v130 row_shr:2 row_mask:0xf bank_mask:0xf
	v_fmac_f32_dpp v167, v59, v131 row_shr:2 row_mask:0xf bank_mask:0xf
	v_mul_f32_e32 v168, 0xbfb8aa3b, v160
	v_mul_f32_e32 v169, 0xbfb8aa3b, v161
	v_mul_f32_e32 v170, 0xbfb8aa3b, v162
	v_mul_f32_e32 v171, 0xbfb8aa3b, v163
	v_exp_f32_e32 v168, v168
	v_exp_f32_e32 v169, v169
	v_exp_f32_e32 v170, v170
	v_exp_f32_e32 v171, v171
	v_add_f32_e32 v168, 1.0, v168
	v_add_f32_e32 v169, 1.0, v169
	v_add_f32_e32 v170, 1.0, v170
	v_add_f32_e32 v171, 1.0, v171
; DI float silu_fast(float x) { return x * __builtin_amdgcn_rcpf(1.f + __expf(-x)); }
; template <int CTRL> DI float dppf(float v) { return __builtin_bit_cast(float, __builtin_amdgcn_update_dpp(0, __builtin_bit_cast(int, v), CTRL, 0xf, 0xf, true)); }
; DI void Epi::fused(const f32x4 (&acc)[2][2][4][2], int pm, int pn, int wr, int wc, int fr, int fq) const {
;     ...
;             for (int m = 0; m < 4; ++m) {
;                 const f32x4 ca = acc[ai][bj][m][0], cb = acc[ai][bj][m][1];
;                 const int row = pm * 256 + ai * 128 + wr * 64 + m * 16 + fr;
;                 float o[4];
; #pragma unroll
;                 for (int e = 0; e < 4; ++e) {
;                     const float a1 = dppf<0x111>(ca[e]) + dppf<0x10F>(pa[e]), a2 = dppf<0x112>(ca[e]) + dppf<0x10E>(pa[e]);
;                     const float b1 = dppf<0x111>(cb[e]) + dppf<0x10F>(pb[e]), b2 = dppf<0x112>(cb[e]) + dppf<0x10E>(pb[e]);
;                     const float ya = fmaf(wa0[e], a2, fmaf(wa1[e], a1, fmaf(wa2[e], ca[e], ba[e])));
;                     const float yb = fmaf(wb0[e], b2, fmaf(wb1[e], b1, fmaf(wb2[e], cb[e], bb[e])));
;                     o[e] = silu_fast(ya) * yb; }
;                 if (m > 0 || fr >= 2) { u32x2 w; w.x = pk2(o[0], o[1]); w.y = pk2(o[2], o[3]); *(u32x2*)(E.d0 + (size_t)row * FFH + j0) = w; }
;                 if ((m == 0 && fr < 2) || (m == 3 && fr >= 14)) { float* hb = E.f0 + ((size_t)(row >> 6) * 4 + (m == 0 ? fr : fr - 12)) * FF2 + ncol; *(f32x4*)hb = ca; *(f32x4*)(hb + 4) = cb; }
	v_rcp_f32_e32 v168, v168
	v_rcp_f32_e32 v169, v169
	v_rcp_f32_e32 v170, v170
	v_rcp_f32_e32 v171, v171
	v_mov_b64_e32 v[174:175], v[224:225]
	v_mul_f32_e32 v160, v160, v168
	v_mul_f32_e32 v161, v161, v169
	v_mul_f32_e32 v162, v162, v170
	v_mul_f32_e32 v163, v163, v171
	v_mul_f32_e32 v160, v164, v160
	v_mul_f32_e32 v161, v165, v161
	v_mul_f32_e32 v162, v166, v162
	v_mul_f32_e32 v163, v167, v163
	v_cvt_pk_bf16_f32 v172, v160, v161
	v_cvt_pk_bf16_f32 v173, v162, v163
	s_and_saveexec_b64 s[76:77], s[38:39]
	global_store_dwordx2 v[174:175], v[172:173], off
	s_or_b64 exec, exec, s[76:77]
	s_ashr_i32 s80, s71, 6
	s_lshl_b32 s80, s80, 2
	s_add_i32 s80, s80, 8
	v_add_u32_e32 v226, s80, v188
	v_mov_b64_e32 v[174:175], s[8:9]
	s_movk_i32 s80, 0x5800
	v_mad_i64_i32 v[174:175], s[78:79], v226, s80, v[174:175]
	v_lshl_add_u64 v[174:175], v[228:229], 2, v[174:175]
	s_and_saveexec_b64 s[76:77], s[40:41]
	global_store_dwordx4 v[174:175], v[60:63], off
	global_store_dwordx4 v[174:175], v[56:59], off offset:16
	s_or_b64 exec, exec, s[76:77]
	v_fma_f32 v208, v152, v52, v156
	v_fma_f32 v209, v153, v53, v157
	v_fma_f32 v210, v154, v54, v158
	v_fma_f32 v211, v155, v55, v159
	v_fma_f32 v212, v144, v40, v148
	v_fma_f32 v213, v145, v41, v149
	v_fma_f32 v214, v146, v42, v150
	v_fma_f32 v215, v147, v43, v151
	v_fmac_f32_dpp v208, v52, v140 row_shr:1 row_mask:0xf bank_mask:0xf
	v_fmac_f32_dpp v209, v53, v141 row_shr:1 row_mask:0xf bank_mask:0xf
	v_fmac_f32_dpp v210, v54, v142 row_shr:1 row_mask:0xf bank_mask:0xf
	v_fmac_f32_dpp v211, v55, v143 row_shr:1 row_mask:0xf bank_mask:0xf
	v_fmac_f32_dpp v212, v40, v132 row_shr:1 row_mask:0xf bank_mask:0xf
	v_fmac_f32_dpp v213, v41, v133 row_shr:1 row_mask:0xf bank_mask:0xf
	v_fmac_f32_dpp v214, v42, v134 row_shr:1 row_mask:0xf bank_mask:0xf
	v_fmac_f32_dpp v215, v43, v135 row_shr:1 row_mask:0xf bank_mask:0xf
	v_fmac_f32_dpp v208, v60, v140 row_shl:15 row_mask:0xf bank_mask:0xf
	v_fmac_f32_dpp v209, v61, v141 row_shl:15 row_mask:0xf bank_mask:0xf
	v_fmac_f32_dpp v210, v62, v142 row_shl:15 row_mask:0xf bank_mask:0xf
	v_fmac_f32_dpp v211, v63, v143 row_shl:15 row_mask:0xf bank_mask:0xf
	v_fmac_f32_dpp v212, v56, v132 row_shl:15 row_mask:0xf bank_mask:0xf
	v_fmac_f32_dpp v213, v57, v133 row_shl:15 row_mask:0xf bank_mask:0xf
	v_fmac_f32_dpp v214, v58, v134 row_shl:15 row_mask:0xf bank_mask:0xf
	v_fmac_f32_dpp v215, v59, v135 row_shl:15 row_mask:0xf bank_mask:0xf
	v_fmac_f32_dpp v208, v52, v136 row_shr:2 row_mask:0xf bank_mask:0xf
	v_fmac_f32_dpp v209, v53, v137 row_shr:2 row_mask:0xf bank_mask:0xf
	v_fmac_f32_dpp v210, v54, v138 row_shr:2 row_mask:0xf bank_mask:0xf
	v_fmac_f32_dpp v211, v55, v139 row_shr:2 row_mask:0xf bank_mask:0xf
	v_fmac_f32_dpp v212, v40, v128 row_shr:2 row_mask:0xf bank_mask:0xf
	v_fmac_f32_dpp v213, v41, v129 row_shr:2 row_mask:0xf bank_mask:0xf
	v_fmac_f32_dpp v214, v42, v130 row_shr:2 row_mask:0xf bank_mask:0xf
	v_fmac_f32_dpp v215, v43, v131 row_shr:2 row_mask:0xf bank_mask:0xf
	v_fmac_f32_dpp v208, v60, v136 row_shl:14 row_mask:0xf bank_mask:0xf
	v_fmac_f32_dpp v209, v61, v137 row_shl:14 row_mask:0xf bank_mask:0xf
	v_fmac_f32_dpp v210, v62, v138 row_shl:14 row_mask:0xf bank_mask:0xf
	v_fmac_f32_dpp v211, v63, v139 row_shl:14 row_mask:0xf bank_mask:0xf
	v_fmac_f32_dpp v212, v56, v128 row_shl:14 row_mask:0xf bank_mask:0xf
	v_fmac_f32_dpp v213, v57, v129 row_shl:14 row_mask:0xf bank_mask:0xf
	v_fmac_f32_dpp v214, v58, v130 row_shl:14 row_mask:0xf bank_mask:0xf
	v_fmac_f32_dpp v215, v59, v131 row_shl:14 row_mask:0xf bank_mask:0xf
	v_mul_f32_e32 v216, 0xbfb8aa3b, v208
	v_mul_f32_e32 v217, 0xbfb8aa3b, v209
	v_mul_f32_e32 v218, 0xbfb8aa3b, v210
	v_mul_f32_e32 v219, 0xbfb8aa3b, v211
	v_exp_f32_e32 v216, v216
	v_exp_f32_e32 v217, v217
	v_exp_f32_e32 v218, v218
	v_exp_f32_e32 v219, v219
	v_add_f32_e32 v216, 1.0, v216
	v_add_f32_e32 v217, 1.0, v217
	v_add_f32_e32 v218, 1.0, v218
	v_add_f32_e32 v219, 1.0, v219
	v_rcp_f32_e32 v216, v216
	v_rcp_f32_e32 v217, v217
	v_rcp_f32_e32 v218, v218
	v_rcp_f32_e32 v219, v219
	s_mov_b32 s80, 0x16000
	s_mov_b32 s81, 0
	v_lshl_add_u64 v[222:223], v[224:225], 0, s[80:81]
	v_mul_f32_e32 v208, v208, v216
	v_mul_f32_e32 v209, v209, v217
	v_mul_f32_e32 v210, v210, v218
	v_mul_f32_e32 v211, v211, v219
	v_mul_f32_e32 v208, v212, v208
	v_mul_f32_e32 v209, v213, v209
	v_mul_f32_e32 v210, v214, v210
	v_mul_f32_e32 v211, v215, v211
	v_cvt_pk_bf16_f32 v220, v208, v209
	v_cvt_pk_bf16_f32 v221, v210, v211
	global_store_dwordx2 v[222:223], v[220:221], off
	v_fma_f32 v160, v152, v36, v156
	v_fma_f32 v161, v153, v37, v157
	v_fma_f32 v162, v154, v38, v158
	v_fma_f32 v163, v155, v39, v159
	v_fma_f32 v164, v144, v16, v148
	v_fma_f32 v165, v145, v17, v149
	v_fma_f32 v166, v146, v18, v150
	v_fma_f32 v167, v147, v19, v151
	v_fmac_f32_dpp v160, v36, v140 row_shr:1 row_mask:0xf bank_mask:0xf
	v_fmac_f32_dpp v161, v37, v141 row_shr:1 row_mask:0xf bank_mask:0xf
	v_fmac_f32_dpp v162, v38, v142 row_shr:1 row_mask:0xf bank_mask:0xf
	v_fmac_f32_dpp v163, v39, v143 row_shr:1 row_mask:0xf bank_mask:0xf
	v_fmac_f32_dpp v164, v16, v132 row_shr:1 row_mask:0xf bank_mask:0xf
	v_fmac_f32_dpp v165, v17, v133 row_shr:1 row_mask:0xf bank_mask:0xf
	v_fmac_f32_dpp v166, v18, v134 row_shr:1 row_mask:0xf bank_mask:0xf
	v_fmac_f32_dpp v167, v19, v135 row_shr:1 row_mask:0xf bank_mask:0xf
	v_fmac_f32_dpp v160, v52, v140 row_shl:15 row_mask:0xf bank_mask:0xf
	v_fmac_f32_dpp v161, v53, v141 row_shl:15 row_mask:0xf bank_mask:0xf
	v_fmac_f32_dpp v162, v54, v142 row_shl:15 row_mask:0xf bank_mask:0xf
	v_fmac_f32_dpp v163, v55, v143 row_shl:15 row_mask:0xf bank_mask:0xf
	v_fmac_f32_dpp v164, v40, v132 row_shl:15 row_mask:0xf bank_mask:0xf
; DI float silu_fast(float x) { return x * __builtin_amdgcn_rcpf(1.f + __expf(-x)); }
; template <int CTRL> DI float dppf(float v) { return __builtin_bit_cast(float, __builtin_amdgcn_update_dpp(0, __builtin_bit_cast(int, v), CTRL, 0xf, 0xf, true)); }
; DI void Epi::fused(const f32x4 (&acc)[2][2][4][2], int pm, int pn, int wr, int wc, int fr, int fq) const {
;     ...
;             for (int m = 0; m < 4; ++m) {
;                 const f32x4 ca = acc[ai][bj][m][0], cb = acc[ai][bj][m][1];
;                 const int row = pm * 256 + ai * 128 + wr * 64 + m * 16 + fr;
;                 float o[4];
; #pragma unroll
;                 for (int e = 0; e < 4; ++e) {
;                     const float a1 = dppf<0x111>(ca[e]) + dppf<0x10F>(pa[e]), a2 = dppf<0x112>(ca[e]) + dppf<0x10E>(pa[e]);
;                     const float b1 = dppf<0x111>(cb[e]) + dppf<0x10F>(pb[e]), b2 = dppf<0x112>(cb[e]) + dppf<0x10E>(pb[e]);
;                     const float ya = fmaf(wa0[e], a2, fmaf(wa1[e], a1, fmaf(wa2[e], ca[e], ba[e])));
;                     const float yb = fmaf(wb0[e], b2, fmaf(wb1[e], b1, fmaf(wb2[e], cb[e], bb[e])));
;                     o[e] = silu_fast(ya) * yb; }
;                 if (m > 0 || fr >= 2) { u32x2 w; w.x = pk2(o[0], o[1]); w.y = pk2(o[2], o[3]); *(u32x2*)(E.d0 + (size_t)row * FFH + j0) = w; }
;                 if ((m == 0 && fr < 2) || (m == 3 && fr >= 14)) { float* hb = E.f0 + ((size_t)(row >> 6) * 4 + (m == 0 ? fr : fr - 12)) * FF2 + ncol; *(f32x4*)hb = ca; *(f32x4*)(hb + 4) = cb; }
	v_fmac_f32_dpp v165, v41, v133 row_shl:15 row_mask:0xf bank_mask:0xf
	v_fmac_f32_dpp v166, v42, v134 row_shl:15 row_mask:0xf bank_mask:0xf
	v_fmac_f32_dpp v167, v43, v135 row_shl:15 row_mask:0xf bank_mask:0xf
	v_fmac_f32_dpp v160, v36, v136 row_shr:2 row_mask:0xf bank_mask:0xf
	v_fmac_f32_dpp v161, v37, v137 row_shr:2 row_mask:0xf bank_mask:0xf
	v_fmac_f32_dpp v162, v38, v138 row_shr:2 row_mask:0xf bank_mask:0xf
	v_fmac_f32_dpp v163, v39, v139 row_shr:2 row_mask:0xf bank_mask:0xf
	v_fmac_f32_dpp v164, v16, v128 row_shr:2 row_mask:0xf bank_mask:0xf
	v_fmac_f32_dpp v165, v17, v129 row_shr:2 row_mask:0xf bank_mask:0xf
	v_fmac_f32_dpp v166, v18, v130 row_shr:2 row_mask:0xf bank_mask:0xf
	v_fmac_f32_dpp v167, v19, v131 row_shr:2 row_mask:0xf bank_mask:0xf
	v_fmac_f32_dpp v160, v52, v136 row_shl:14 row_mask:0xf bank_mask:0xf
	v_fmac_f32_dpp v161, v53, v137 row_shl:14 row_mask:0xf bank_mask:0xf
	v_fmac_f32_dpp v162, v54, v138 row_shl:14 row_mask:0xf bank_mask:0xf
	v_fmac_f32_dpp v163, v55, v139 row_shl:14 row_mask:0xf bank_mask:0xf
	v_fmac_f32_dpp v164, v40, v128 row_shl:14 row_mask:0xf bank_mask:0xf
	v_fmac_f32_dpp v165, v41, v129 row_shl:14 row_mask:0xf bank_mask:0xf
	v_fmac_f32_dpp v166, v42, v130 row_shl:14 row_mask:0xf bank_mask:0xf
	v_fmac_f32_dpp v167, v43, v131 row_shl:14 row_mask:0xf bank_mask:0xf
	v_mul_f32_e32 v168, 0xbfb8aa3b, v160
	v_mul_f32_e32 v169, 0xbfb8aa3b, v161
	v_mul_f32_e32 v170, 0xbfb8aa3b, v162
	v_mul_f32_e32 v171, 0xbfb8aa3b, v163
	v_exp_f32_e32 v168, v168
	v_exp_f32_e32 v169, v169
	v_exp_f32_e32 v170, v170
	v_exp_f32_e32 v171, v171
	v_add_f32_e32 v168, 1.0, v168
	v_add_f32_e32 v169, 1.0, v169
	v_add_f32_e32 v170, 1.0, v170
	v_add_f32_e32 v171, 1.0, v171
	v_rcp_f32_e32 v168, v168
	v_rcp_f32_e32 v169, v169
	v_rcp_f32_e32 v170, v170
	v_rcp_f32_e32 v171, v171
	s_mov_b32 s80, 0x2c000
	s_mov_b32 s81, 0
	v_lshl_add_u64 v[174:175], v[224:225], 0, s[80:81]
	v_mul_f32_e32 v160, v160, v168
	v_mul_f32_e32 v161, v161, v169
	v_mul_f32_e32 v162, v162, v170
	v_mul_f32_e32 v163, v163, v171
	v_mul_f32_e32 v160, v164, v160
	v_mul_f32_e32 v161, v165, v161
	v_mul_f32_e32 v162, v166, v162
	v_mul_f32_e32 v163, v167, v163
	v_cvt_pk_bf16_f32 v172, v160, v161
	v_cvt_pk_bf16_f32 v173, v162, v163
	global_store_dwordx2 v[174:175], v[172:173], off
	v_fma_f32 v208, v152, v12, v156
	v_fma_f32 v209, v153, v13, v157
	v_fma_f32 v210, v154, v14, v158
	v_fma_f32 v211, v155, v15, v159
	v_fma_f32 v212, v144, v0, v148
	v_fma_f32 v213, v145, v1, v149
	v_fma_f32 v214, v146, v2, v150
	v_fma_f32 v215, v147, v3, v151
	v_fmac_f32_dpp v208, v12, v140 row_shr:1 row_mask:0xf bank_mask:0xf
	v_fmac_f32_dpp v209, v13, v141 row_shr:1 row_mask:0xf bank_mask:0xf
	v_fmac_f32_dpp v210, v14, v142 row_shr:1 row_mask:0xf bank_mask:0xf
	v_fmac_f32_dpp v211, v15, v143 row_shr:1 row_mask:0xf bank_mask:0xf
	v_fmac_f32_dpp v212, v0, v132 row_shr:1 row_mask:0xf bank_mask:0xf
	v_fmac_f32_dpp v213, v1, v133 row_shr:1 row_mask:0xf bank_mask:0xf
	v_fmac_f32_dpp v214, v2, v134 row_shr:1 row_mask:0xf bank_mask:0xf
	v_fmac_f32_dpp v215, v3, v135 row_shr:1 row_mask:0xf bank_mask:0xf
	v_fmac_f32_dpp v208, v36, v140 row_shl:15 row_mask:0xf bank_mask:0xf
	v_fmac_f32_dpp v209, v37, v141 row_shl:15 row_mask:0xf bank_mask:0xf
	v_fmac_f32_dpp v210, v38, v142 row_shl:15 row_mask:0xf bank_mask:0xf
	v_fmac_f32_dpp v211, v39, v143 row_shl:15 row_mask:0xf bank_mask:0xf
	v_fmac_f32_dpp v212, v16, v132 row_shl:15 row_mask:0xf bank_mask:0xf
	v_fmac_f32_dpp v213, v17, v133 row_shl:15 row_mask:0xf bank_mask:0xf
	v_fmac_f32_dpp v214, v18, v134 row_shl:15 row_mask:0xf bank_mask:0xf
	v_fmac_f32_dpp v215, v19, v135 row_shl:15 row_mask:0xf bank_mask:0xf
	v_fmac_f32_dpp v208, v12, v136 row_shr:2 row_mask:0xf bank_mask:0xf
	v_fmac_f32_dpp v209, v13, v137 row_shr:2 row_mask:0xf bank_mask:0xf
	v_fmac_f32_dpp v210, v14, v138 row_shr:2 row_mask:0xf bank_mask:0xf
	v_fmac_f32_dpp v211, v15, v139 row_shr:2 row_mask:0xf bank_mask:0xf
	v_fmac_f32_dpp v212, v0, v128 row_shr:2 row_mask:0xf bank_mask:0xf
	v_fmac_f32_dpp v213, v1, v129 row_shr:2 row_mask:0xf bank_mask:0xf
	v_fmac_f32_dpp v214, v2, v130 row_shr:2 row_mask:0xf bank_mask:0xf
	v_fmac_f32_dpp v215, v3, v131 row_shr:2 row_mask:0xf bank_mask:0xf
	v_fmac_f32_dpp v208, v36, v136 row_shl:14 row_mask:0xf bank_mask:0xf
	v_fmac_f32_dpp v209, v37, v137 row_shl:14 row_mask:0xf bank_mask:0xf
	v_fmac_f32_dpp v210, v38, v138 row_shl:14 row_mask:0xf bank_mask:0xf
	v_fmac_f32_dpp v211, v39, v139 row_shl:14 row_mask:0xf bank_mask:0xf
	v_fmac_f32_dpp v212, v16, v128 row_shl:14 row_mask:0xf bank_mask:0xf
	v_fmac_f32_dpp v213, v17, v129 row_shl:14 row_mask:0xf bank_mask:0xf
	v_fmac_f32_dpp v214, v18, v130 row_shl:14 row_mask:0xf bank_mask:0xf
	v_fmac_f32_dpp v215, v19, v131 row_shl:14 row_mask:0xf bank_mask:0xf
	v_mul_f32_e32 v216, 0xbfb8aa3b, v208
	v_mul_f32_e32 v217, 0xbfb8aa3b, v209
	v_mul_f32_e32 v218, 0xbfb8aa3b, v210
	v_mul_f32_e32 v219, 0xbfb8aa3b, v211
	v_exp_f32_e32 v216, v216
	v_exp_f32_e32 v217, v217
	v_exp_f32_e32 v218, v218
	v_exp_f32_e32 v219, v219
	v_add_f32_e32 v216, 1.0, v216
	v_add_f32_e32 v217, 1.0, v217
	v_add_f32_e32 v218, 1.0, v218
	v_add_f32_e32 v219, 1.0, v219
	v_rcp_f32_e32 v216, v216
	v_rcp_f32_e32 v217, v217
	v_rcp_f32_e32 v218, v218
	v_rcp_f32_e32 v219, v219
	s_mov_b32 s80, 0x42000
	s_mov_b32 s81, 0
	v_lshl_add_u64 v[222:223], v[224:225], 0, s[80:81]
	v_mul_f32_e32 v208, v208, v216
	v_mul_f32_e32 v209, v209, v217
	v_mul_f32_e32 v210, v210, v218
	v_mul_f32_e32 v211, v211, v219
	v_mul_f32_e32 v208, v212, v208
	v_mul_f32_e32 v209, v213, v209
	v_mul_f32_e32 v210, v214, v210
	v_mul_f32_e32 v211, v215, v211
	v_cvt_pk_bf16_f32 v220, v208, v209
	v_cvt_pk_bf16_f32 v221, v210, v211
	global_store_dwordx2 v[222:223], v[220:221], off
	s_ashr_i32 s80, s71, 6
	s_lshl_b32 s80, s80, 2
	s_add_i32 s80, s80, 8
	v_add_u32_e32 v226, s80, v190
	v_mov_b64_e32 v[222:223], s[8:9]
	s_movk_i32 s80, 0x5800
	v_mad_i64_i32 v[222:223], s[78:79], v226, s80, v[222:223]
	v_lshl_add_u64 v[222:223], v[228:229], 2, v[222:223]
	s_and_saveexec_b64 s[76:77], s[42:43]
	global_store_dwordx4 v[222:223], v[12:15], off
	global_store_dwordx4 v[222:223], v[0:3], off offset:16
	s_or_b64 exec, exec, s[76:77]
	v_mov_b32_e32 v228, v199
	v_mov_b64_e32 v[224:225], s[12:13]
	s_movk_i32 s80, 0x1600
	v_mad_i64_i32 v[224:225], s[78:79], v228, s80, v[224:225]
	v_add_u32_e32 v228, 128, v240
	v_mov_b32_e32 v229, 0
	v_lshl_add_u64 v[224:225], v[228:229], 0, v[224:225]
	s_waitcnt vmcnt(8)
; DI float silu_fast(float x) { return x * __builtin_amdgcn_rcpf(1.f + __expf(-x)); }
; template <int CTRL> DI float dppf(float v) { return __builtin_bit_cast(float, __builtin_amdgcn_update_dpp(0, __builtin_bit_cast(int, v), CTRL, 0xf, 0xf, true)); }
; DI void Epi::fused(const f32x4 (&acc)[2][2][4][2], int pm, int pn, int wr, int wc, int fr, int fq) const {
;     ...
;             for (int m = 0; m < 4; ++m) {
;                 const f32x4 ca = acc[ai][bj][m][0], cb = acc[ai][bj][m][1];
;                 const int row = pm * 256 + ai * 128 + wr * 64 + m * 16 + fr;
;                 float o[4];
; #pragma unroll
;                 for (int e = 0; e < 4; ++e) {
;                     const float a1 = dppf<0x111>(ca[e]) + dppf<0x10F>(pa[e]), a2 = dppf<0x112>(ca[e]) + dppf<0x10E>(pa[e]);
;                     const float b1 = dppf<0x111>(cb[e]) + dppf<0x10F>(pb[e]), b2 = dppf<0x112>(cb[e]) + dppf<0x10E>(pb[e]);
;                     const float ya = fmaf(wa0[e], a2, fmaf(wa1[e], a1, fmaf(wa2[e], ca[e], ba[e])));
;                     const float yb = fmaf(wb0[e], b2, fmaf(wb1[e], b1, fmaf(wb2[e], cb[e], bb[e])));
;                     o[e] = silu_fast(ya) * yb; }
;                 if (m > 0 || fr >= 2) { u32x2 w; w.x = pk2(o[0], o[1]); w.y = pk2(o[2], o[3]); *(u32x2*)(E.d0 + (size_t)row * FFH + j0) = w; }
;                 if ((m == 0 && fr < 2) || (m == 3 && fr >= 14)) { float* hb = E.f0 + ((size_t)(row >> 6) * 4 + (m == 0 ? fr : fr - 12)) * FF2 + ncol; *(f32x4*)hb = ca; *(f32x4*)(hb + 4) = cb; }
	v_fma_f32 v160, v100, v112, v124
	v_fma_f32 v161, v101, v113, v125
	v_fma_f32 v162, v102, v114, v126
	v_fma_f32 v163, v103, v115, v127
	v_fma_f32 v164, v120, v108, v72
	v_fma_f32 v165, v121, v109, v73
	v_fma_f32 v166, v122, v110, v74
	v_fma_f32 v167, v123, v111, v75
	v_fmac_f32_dpp v160, v112, v88 row_shr:1 row_mask:0xf bank_mask:0xf
	v_fmac_f32_dpp v161, v113, v89 row_shr:1 row_mask:0xf bank_mask:0xf
	v_fmac_f32_dpp v162, v114, v90 row_shr:1 row_mask:0xf bank_mask:0xf
	v_fmac_f32_dpp v163, v115, v91 row_shr:1 row_mask:0xf bank_mask:0xf
	v_fmac_f32_dpp v164, v108, v116 row_shr:1 row_mask:0xf bank_mask:0xf
	v_fmac_f32_dpp v165, v109, v117 row_shr:1 row_mask:0xf bank_mask:0xf
	v_fmac_f32_dpp v166, v110, v118 row_shr:1 row_mask:0xf bank_mask:0xf
	v_fmac_f32_dpp v167, v111, v119 row_shr:1 row_mask:0xf bank_mask:0xf
	v_fmac_f32_dpp v160, v112, v84 row_shr:2 row_mask:0xf bank_mask:0xf
	v_fmac_f32_dpp v161, v113, v85 row_shr:2 row_mask:0xf bank_mask:0xf
	v_fmac_f32_dpp v162, v114, v86 row_shr:2 row_mask:0xf bank_mask:0xf
	v_fmac_f32_dpp v163, v115, v87 row_shr:2 row_mask:0xf bank_mask:0xf
	v_fmac_f32_dpp v164, v108, v104 row_shr:2 row_mask:0xf bank_mask:0xf
	v_fmac_f32_dpp v165, v109, v105 row_shr:2 row_mask:0xf bank_mask:0xf
	v_fmac_f32_dpp v166, v110, v106 row_shr:2 row_mask:0xf bank_mask:0xf
	v_fmac_f32_dpp v167, v111, v107 row_shr:2 row_mask:0xf bank_mask:0xf
	v_mul_f32_e32 v168, 0xbfb8aa3b, v160
	v_mul_f32_e32 v169, 0xbfb8aa3b, v161
	v_mul_f32_e32 v170, 0xbfb8aa3b, v162
	v_mul_f32_e32 v171, 0xbfb8aa3b, v163
	v_exp_f32_e32 v168, v168
	v_exp_f32_e32 v169, v169
	v_exp_f32_e32 v170, v170
	v_exp_f32_e32 v171, v171
	v_add_f32_e32 v168, 1.0, v168
	v_add_f32_e32 v169, 1.0, v169
	v_add_f32_e32 v170, 1.0, v170
	v_add_f32_e32 v171, 1.0, v171
	v_rcp_f32_e32 v168, v168
	v_rcp_f32_e32 v169, v169
	v_rcp_f32_e32 v170, v170
	v_rcp_f32_e32 v171, v171
	v_mov_b64_e32 v[174:175], v[224:225]
	v_mul_f32_e32 v160, v160, v168
	v_mul_f32_e32 v161, v161, v169
	v_mul_f32_e32 v162, v162, v170
	v_mul_f32_e32 v163, v163, v171
	v_mul_f32_e32 v160, v164, v160
	v_mul_f32_e32 v161, v165, v161
	v_mul_f32_e32 v162, v166, v162
	v_mul_f32_e32 v163, v167, v163
	v_cvt_pk_bf16_f32 v172, v160, v161
	v_cvt_pk_bf16_f32 v173, v162, v163
	s_and_saveexec_b64 s[76:77], s[38:39]
	global_store_dwordx2 v[174:175], v[172:173], off
	s_or_b64 exec, exec, s[76:77]
	s_ashr_i32 s80, s71, 6
	s_lshl_b32 s80, s80, 2
	v_add_u32_e32 v226, s80, v188
	v_mov_b64_e32 v[174:175], s[8:9]
	s_movk_i32 s80, 0x5800
	v_mad_i64_i32 v[174:175], s[78:79], v226, s80, v[174:175]
	v_lshl_add_u64 v[174:175], v[228:229], 2, v[174:175]
	s_and_saveexec_b64 s[76:77], s[40:41]
	global_store_dwordx4 v[174:175], v[112:115], off
	global_store_dwordx4 v[174:175], v[108:111], off offset:16
	s_or_b64 exec, exec, s[76:77]
	v_fma_f32 v208, v100, v96, v124
	v_fma_f32 v209, v101, v97, v125
	v_fma_f32 v210, v102, v98, v126
	v_fma_f32 v211, v103, v99, v127
	v_fma_f32 v212, v120, v92, v72
	v_fma_f32 v213, v121, v93, v73
	v_fma_f32 v214, v122, v94, v74
	v_fma_f32 v215, v123, v95, v75
	v_fmac_f32_dpp v208, v96, v88 row_shr:1 row_mask:0xf bank_mask:0xf
	v_fmac_f32_dpp v209, v97, v89 row_shr:1 row_mask:0xf bank_mask:0xf
	v_fmac_f32_dpp v210, v98, v90 row_shr:1 row_mask:0xf bank_mask:0xf
	v_fmac_f32_dpp v211, v99, v91 row_shr:1 row_mask:0xf bank_mask:0xf
	v_fmac_f32_dpp v212, v92, v116 row_shr:1 row_mask:0xf bank_mask:0xf
	v_fmac_f32_dpp v213, v93, v117 row_shr:1 row_mask:0xf bank_mask:0xf
	v_fmac_f32_dpp v214, v94, v118 row_shr:1 row_mask:0xf bank_mask:0xf
	v_fmac_f32_dpp v215, v95, v119 row_shr:1 row_mask:0xf bank_mask:0xf
	v_fmac_f32_dpp v208, v112, v88 row_shl:15 row_mask:0xf bank_mask:0xf
	v_fmac_f32_dpp v209, v113, v89 row_shl:15 row_mask:0xf bank_mask:0xf
	v_fmac_f32_dpp v210, v114, v90 row_shl:15 row_mask:0xf bank_mask:0xf
	v_fmac_f32_dpp v211, v115, v91 row_shl:15 row_mask:0xf bank_mask:0xf
	v_fmac_f32_dpp v212, v108, v116 row_shl:15 row_mask:0xf bank_mask:0xf
	v_fmac_f32_dpp v213, v109, v117 row_shl:15 row_mask:0xf bank_mask:0xf
	v_fmac_f32_dpp v214, v110, v118 row_shl:15 row_mask:0xf bank_mask:0xf
	v_fmac_f32_dpp v215, v111, v119 row_shl:15 row_mask:0xf bank_mask:0xf
	v_fmac_f32_dpp v208, v96, v84 row_shr:2 row_mask:0xf bank_mask:0xf
	v_fmac_f32_dpp v209, v97, v85 row_shr:2 row_mask:0xf bank_mask:0xf
	v_fmac_f32_dpp v210, v98, v86 row_shr:2 row_mask:0xf bank_mask:0xf
	v_fmac_f32_dpp v211, v99, v87 row_shr:2 row_mask:0xf bank_mask:0xf
	v_fmac_f32_dpp v212, v92, v104 row_shr:2 row_mask:0xf bank_mask:0xf
	v_fmac_f32_dpp v213, v93, v105 row_shr:2 row_mask:0xf bank_mask:0xf
	v_fmac_f32_dpp v214, v94, v106 row_shr:2 row_mask:0xf bank_mask:0xf
	v_fmac_f32_dpp v215, v95, v107 row_shr:2 row_mask:0xf bank_mask:0xf
	v_fmac_f32_dpp v208, v112, v84 row_shl:14 row_mask:0xf bank_mask:0xf
	v_fmac_f32_dpp v209, v113, v85 row_shl:14 row_mask:0xf bank_mask:0xf
	v_fmac_f32_dpp v210, v114, v86 row_shl:14 row_mask:0xf bank_mask:0xf
	v_fmac_f32_dpp v211, v115, v87 row_shl:14 row_mask:0xf bank_mask:0xf
	v_fmac_f32_dpp v212, v108, v104 row_shl:14 row_mask:0xf bank_mask:0xf
	v_fmac_f32_dpp v213, v109, v105 row_shl:14 row_mask:0xf bank_mask:0xf
	v_fmac_f32_dpp v214, v110, v106 row_shl:14 row_mask:0xf bank_mask:0xf
	v_fmac_f32_dpp v215, v111, v107 row_shl:14 row_mask:0xf bank_mask:0xf
	v_mul_f32_e32 v216, 0xbfb8aa3b, v208
	v_mul_f32_e32 v217, 0xbfb8aa3b, v209
	v_mul_f32_e32 v218, 0xbfb8aa3b, v210
	v_mul_f32_e32 v219, 0xbfb8aa3b, v211
	v_exp_f32_e32 v216, v216
	v_exp_f32_e32 v217, v217
	v_exp_f32_e32 v218, v218
	v_exp_f32_e32 v219, v219
	v_add_f32_e32 v216, 1.0, v216
	v_add_f32_e32 v217, 1.0, v217
	v_add_f32_e32 v218, 1.0, v218
	v_add_f32_e32 v219, 1.0, v219
; DI float silu_fast(float x) { return x * __builtin_amdgcn_rcpf(1.f + __expf(-x)); }
; template <int CTRL> DI float dppf(float v) { return __builtin_bit_cast(float, __builtin_amdgcn_update_dpp(0, __builtin_bit_cast(int, v), CTRL, 0xf, 0xf, true)); }
; DI void Epi::fused(const f32x4 (&acc)[2][2][4][2], int pm, int pn, int wr, int wc, int fr, int fq) const {
;     ...
;             for (int m = 0; m < 4; ++m) {
;                 const f32x4 ca = acc[ai][bj][m][0], cb = acc[ai][bj][m][1];
;                 const int row = pm * 256 + ai * 128 + wr * 64 + m * 16 + fr;
;                 float o[4];
; #pragma unroll
;                 for (int e = 0; e < 4; ++e) {
;                     const float a1 = dppf<0x111>(ca[e]) + dppf<0x10F>(pa[e]), a2 = dppf<0x112>(ca[e]) + dppf<0x10E>(pa[e]);
;                     const float b1 = dppf<0x111>(cb[e]) + dppf<0x10F>(pb[e]), b2 = dppf<0x112>(cb[e]) + dppf<0x10E>(pb[e]);
;                     const float ya = fmaf(wa0[e], a2, fmaf(wa1[e], a1, fmaf(wa2[e], ca[e], ba[e])));
;                     const float yb = fmaf(wb0[e], b2, fmaf(wb1[e], b1, fmaf(wb2[e], cb[e], bb[e])));
;                     o[e] = silu_fast(ya) * yb; }
;                 if (m > 0 || fr >= 2) { u32x2 w; w.x = pk2(o[0], o[1]); w.y = pk2(o[2], o[3]); *(u32x2*)(E.d0 + (size_t)row * FFH + j0) = w; }
	v_rcp_f32_e32 v216, v216
	v_rcp_f32_e32 v217, v217
	v_rcp_f32_e32 v218, v218
	v_rcp_f32_e32 v219, v219
	s_mov_b32 s80, 0x16000
	s_mov_b32 s81, 0
	v_lshl_add_u64 v[222:223], v[224:225], 0, s[80:81]
	v_mul_f32_e32 v208, v208, v216
	v_mul_f32_e32 v209, v209, v217
	v_mul_f32_e32 v210, v210, v218
	v_mul_f32_e32 v211, v211, v219
	v_mul_f32_e32 v208, v212, v208
	v_mul_f32_e32 v209, v213, v209
	v_mul_f32_e32 v210, v214, v210
	v_mul_f32_e32 v211, v215, v211
	v_cvt_pk_bf16_f32 v220, v208, v209
	v_cvt_pk_bf16_f32 v221, v210, v211
	global_store_dwordx2 v[222:223], v[220:221], off
	v_fma_f32 v160, v100, v80, v124
	v_fma_f32 v161, v101, v81, v125
	v_fma_f32 v162, v102, v82, v126
	v_fma_f32 v163, v103, v83, v127
	v_fma_f32 v164, v120, v76, v72
	v_fma_f32 v165, v121, v77, v73
	v_fma_f32 v166, v122, v78, v74
	v_fma_f32 v167, v123, v79, v75
	v_fmac_f32_dpp v160, v80, v88 row_shr:1 row_mask:0xf bank_mask:0xf
	v_fmac_f32_dpp v161, v81, v89 row_shr:1 row_mask:0xf bank_mask:0xf
	v_fmac_f32_dpp v162, v82, v90 row_shr:1 row_mask:0xf bank_mask:0xf
	v_fmac_f32_dpp v163, v83, v91 row_shr:1 row_mask:0xf bank_mask:0xf
	v_fmac_f32_dpp v164, v76, v116 row_shr:1 row_mask:0xf bank_mask:0xf
	v_fmac_f32_dpp v165, v77, v117 row_shr:1 row_mask:0xf bank_mask:0xf
	v_fmac_f32_dpp v166, v78, v118 row_shr:1 row_mask:0xf bank_mask:0xf
	v_fmac_f32_dpp v167, v79, v119 row_shr:1 row_mask:0xf bank_mask:0xf
	v_fmac_f32_dpp v160, v96, v88 row_shl:15 row_mask:0xf bank_mask:0xf
	v_fmac_f32_dpp v161, v97, v89 row_shl:15 row_mask:0xf bank_mask:0xf
	v_fmac_f32_dpp v162, v98, v90 row_shl:15 row_mask:0xf bank_mask:0xf
	v_fmac_f32_dpp v163, v99, v91 row_shl:15 row_mask:0xf bank_mask:0xf
	v_fmac_f32_dpp v164, v92, v116 row_shl:15 row_mask:0xf bank_mask:0xf
	v_fmac_f32_dpp v165, v93, v117 row_shl:15 row_mask:0xf bank_mask:0xf
	v_fmac_f32_dpp v166, v94, v118 row_shl:15 row_mask:0xf bank_mask:0xf
	v_fmac_f32_dpp v167, v95, v119 row_shl:15 row_mask:0xf bank_mask:0xf
	v_fmac_f32_dpp v160, v80, v84 row_shr:2 row_mask:0xf bank_mask:0xf
	v_fmac_f32_dpp v161, v81, v85 row_shr:2 row_mask:0xf bank_mask:0xf
	v_fmac_f32_dpp v162, v82, v86 row_shr:2 row_mask:0xf bank_mask:0xf
	v_fmac_f32_dpp v163, v83, v87 row_shr:2 row_mask:0xf bank_mask:0xf
	v_fmac_f32_dpp v164, v76, v104 row_shr:2 row_mask:0xf bank_mask:0xf
	v_fmac_f32_dpp v165, v77, v105 row_shr:2 row_mask:0xf bank_mask:0xf
	v_fmac_f32_dpp v166, v78, v106 row_shr:2 row_mask:0xf bank_mask:0xf
	v_fmac_f32_dpp v167, v79, v107 row_shr:2 row_mask:0xf bank_mask:0xf
	v_fmac_f32_dpp v160, v96, v84 row_shl:14 row_mask:0xf bank_mask:0xf
	v_fmac_f32_dpp v161, v97, v85 row_shl:14 row_mask:0xf bank_mask:0xf
	v_fmac_f32_dpp v162, v98, v86 row_shl:14 row_mask:0xf bank_mask:0xf
	v_fmac_f32_dpp v163, v99, v87 row_shl:14 row_mask:0xf bank_mask:0xf
	v_fmac_f32_dpp v164, v92, v104 row_shl:14 row_mask:0xf bank_mask:0xf
	v_fmac_f32_dpp v165, v93, v105 row_shl:14 row_mask:0xf bank_mask:0xf
	v_fmac_f32_dpp v166, v94, v106 row_shl:14 row_mask:0xf bank_mask:0xf
	v_fmac_f32_dpp v167, v95, v107 row_shl:14 row_mask:0xf bank_mask:0xf
	v_mul_f32_e32 v168, 0xbfb8aa3b, v160
	v_mul_f32_e32 v169, 0xbfb8aa3b, v161
	v_mul_f32_e32 v170, 0xbfb8aa3b, v162
	v_mul_f32_e32 v171, 0xbfb8aa3b, v163
	v_exp_f32_e32 v168, v168
	v_exp_f32_e32 v169, v169
	v_exp_f32_e32 v170, v170
	v_exp_f32_e32 v171, v171
	v_add_f32_e32 v168, 1.0, v168
	v_add_f32_e32 v169, 1.0, v169
	v_add_f32_e32 v170, 1.0, v170
	v_add_f32_e32 v171, 1.0, v171
	v_rcp_f32_e32 v168, v168
	v_rcp_f32_e32 v169, v169
	v_rcp_f32_e32 v170, v170
	v_rcp_f32_e32 v171, v171
	s_mov_b32 s80, 0x2c000
	s_mov_b32 s81, 0
	v_lshl_add_u64 v[174:175], v[224:225], 0, s[80:81]
	v_mul_f32_e32 v160, v160, v168
	v_mul_f32_e32 v161, v161, v169
	v_mul_f32_e32 v162, v162, v170
	v_mul_f32_e32 v163, v163, v171
	v_mul_f32_e32 v160, v164, v160
	v_mul_f32_e32 v161, v165, v161
	v_mul_f32_e32 v162, v166, v162
	v_mul_f32_e32 v163, v167, v163
	v_cvt_pk_bf16_f32 v172, v160, v161
	v_cvt_pk_bf16_f32 v173, v162, v163
	global_store_dwordx2 v[174:175], v[172:173], off
	v_fma_f32 v208, v100, v68, v124
	v_fma_f32 v209, v101, v69, v125
	v_fma_f32 v210, v102, v70, v126
	v_fma_f32 v211, v103, v71, v127
	v_fma_f32 v212, v120, v64, v72
	v_fma_f32 v213, v121, v65, v73
	v_fma_f32 v214, v122, v66, v74
	v_fma_f32 v215, v123, v67, v75
	v_fmac_f32_dpp v208, v68, v88 row_shr:1 row_mask:0xf bank_mask:0xf
	v_fmac_f32_dpp v209, v69, v89 row_shr:1 row_mask:0xf bank_mask:0xf
	v_fmac_f32_dpp v210, v70, v90 row_shr:1 row_mask:0xf bank_mask:0xf
	v_fmac_f32_dpp v211, v71, v91 row_shr:1 row_mask:0xf bank_mask:0xf
	v_fmac_f32_dpp v212, v64, v116 row_shr:1 row_mask:0xf bank_mask:0xf
	v_fmac_f32_dpp v213, v65, v117 row_shr:1 row_mask:0xf bank_mask:0xf
	v_fmac_f32_dpp v214, v66, v118 row_shr:1 row_mask:0xf bank_mask:0xf
	v_fmac_f32_dpp v215, v67, v119 row_shr:1 row_mask:0xf bank_mask:0xf
	v_fmac_f32_dpp v208, v80, v88 row_shl:15 row_mask:0xf bank_mask:0xf
	v_fmac_f32_dpp v209, v81, v89 row_shl:15 row_mask:0xf bank_mask:0xf
	v_fmac_f32_dpp v210, v82, v90 row_shl:15 row_mask:0xf bank_mask:0xf
	v_fmac_f32_dpp v211, v83, v91 row_shl:15 row_mask:0xf bank_mask:0xf
	v_fmac_f32_dpp v212, v76, v116 row_shl:15 row_mask:0xf bank_mask:0xf
	v_fmac_f32_dpp v213, v77, v117 row_shl:15 row_mask:0xf bank_mask:0xf
	v_fmac_f32_dpp v214, v78, v118 row_shl:15 row_mask:0xf bank_mask:0xf
	v_fmac_f32_dpp v215, v79, v119 row_shl:15 row_mask:0xf bank_mask:0xf
	v_fmac_f32_dpp v208, v68, v84 row_shr:2 row_mask:0xf bank_mask:0xf
	v_fmac_f32_dpp v209, v69, v85 row_shr:2 row_mask:0xf bank_mask:0xf
	v_fmac_f32_dpp v210, v70, v86 row_shr:2 row_mask:0xf bank_mask:0xf
	v_fmac_f32_dpp v211, v71, v87 row_shr:2 row_mask:0xf bank_mask:0xf
; DI float silu_fast(float x) { return x * __builtin_amdgcn_rcpf(1.f + __expf(-x)); }
; template <int CTRL> DI float dppf(float v) { return __builtin_bit_cast(float, __builtin_amdgcn_update_dpp(0, __builtin_bit_cast(int, v), CTRL, 0xf, 0xf, true)); }
; DI void Epi::fused(const f32x4 (&acc)[2][2][4][2], int pm, int pn, int wr, int wc, int fr, int fq) const {
;     ...
;             for (int m = 0; m < 4; ++m) {
;                 const f32x4 ca = acc[ai][bj][m][0], cb = acc[ai][bj][m][1];
;                 const int row = pm * 256 + ai * 128 + wr * 64 + m * 16 + fr;
;                 float o[4];
; #pragma unroll
;                 for (int e = 0; e < 4; ++e) {
;                     const float a1 = dppf<0x111>(ca[e]) + dppf<0x10F>(pa[e]), a2 = dppf<0x112>(ca[e]) + dppf<0x10E>(pa[e]);
;                     const float b1 = dppf<0x111>(cb[e]) + dppf<0x10F>(pb[e]), b2 = dppf<0x112>(cb[e]) + dppf<0x10E>(pb[e]);
;                     const float ya = fmaf(wa0[e], a2, fmaf(wa1[e], a1, fmaf(wa2[e], ca[e], ba[e])));
;                     const float yb = fmaf(wb0[e], b2, fmaf(wb1[e], b1, fmaf(wb2[e], cb[e], bb[e])));
;                     o[e] = silu_fast(ya) * yb; }
;                 if (m > 0 || fr >= 2) { u32x2 w; w.x = pk2(o[0], o[1]); w.y = pk2(o[2], o[3]); *(u32x2*)(E.d0 + (size_t)row * FFH + j0) = w; }
;                 if ((m == 0 && fr < 2) || (m == 3 && fr >= 14)) { float* hb = E.f0 + ((size_t)(row >> 6) * 4 + (m == 0 ? fr : fr - 12)) * FF2 + ncol; *(f32x4*)hb = ca; *(f32x4*)(hb + 4) = cb; }
	v_fmac_f32_dpp v212, v64, v104 row_shr:2 row_mask:0xf bank_mask:0xf
	v_fmac_f32_dpp v213, v65, v105 row_shr:2 row_mask:0xf bank_mask:0xf
	v_fmac_f32_dpp v214, v66, v106 row_shr:2 row_mask:0xf bank_mask:0xf
	v_fmac_f32_dpp v215, v67, v107 row_shr:2 row_mask:0xf bank_mask:0xf
	v_fmac_f32_dpp v208, v80, v84 row_shl:14 row_mask:0xf bank_mask:0xf
	v_fmac_f32_dpp v209, v81, v85 row_shl:14 row_mask:0xf bank_mask:0xf
	v_fmac_f32_dpp v210, v82, v86 row_shl:14 row_mask:0xf bank_mask:0xf
	v_fmac_f32_dpp v211, v83, v87 row_shl:14 row_mask:0xf bank_mask:0xf
	v_fmac_f32_dpp v212, v76, v104 row_shl:14 row_mask:0xf bank_mask:0xf
	v_fmac_f32_dpp v213, v77, v105 row_shl:14 row_mask:0xf bank_mask:0xf
	v_fmac_f32_dpp v214, v78, v106 row_shl:14 row_mask:0xf bank_mask:0xf
	v_fmac_f32_dpp v215, v79, v107 row_shl:14 row_mask:0xf bank_mask:0xf
	v_mul_f32_e32 v216, 0xbfb8aa3b, v208
	v_mul_f32_e32 v217, 0xbfb8aa3b, v209
	v_mul_f32_e32 v218, 0xbfb8aa3b, v210
	v_mul_f32_e32 v219, 0xbfb8aa3b, v211
	v_exp_f32_e32 v216, v216
	v_exp_f32_e32 v217, v217
	v_exp_f32_e32 v218, v218
	v_exp_f32_e32 v219, v219
	v_add_f32_e32 v216, 1.0, v216
	v_add_f32_e32 v217, 1.0, v217
	v_add_f32_e32 v218, 1.0, v218
	v_add_f32_e32 v219, 1.0, v219
	v_rcp_f32_e32 v216, v216
	v_rcp_f32_e32 v217, v217
	v_rcp_f32_e32 v218, v218
	v_rcp_f32_e32 v219, v219
	s_mov_b32 s80, 0x42000
	s_mov_b32 s81, 0
	v_lshl_add_u64 v[222:223], v[224:225], 0, s[80:81]
	v_mul_f32_e32 v208, v208, v216
	v_mul_f32_e32 v209, v209, v217
	v_mul_f32_e32 v210, v210, v218
	v_mul_f32_e32 v211, v211, v219
	v_mul_f32_e32 v208, v212, v208
	v_mul_f32_e32 v209, v213, v209
	v_mul_f32_e32 v210, v214, v210
	v_mul_f32_e32 v211, v215, v211
	v_cvt_pk_bf16_f32 v220, v208, v209
	v_cvt_pk_bf16_f32 v221, v210, v211
	global_store_dwordx2 v[222:223], v[220:221], off
	s_ashr_i32 s80, s71, 6
	s_lshl_b32 s80, s80, 2
	v_add_u32_e32 v226, s80, v190
	v_mov_b64_e32 v[222:223], s[8:9]
	s_movk_i32 s80, 0x5800
	v_mad_i64_i32 v[222:223], s[78:79], v226, s80, v[222:223]
	v_lshl_add_u64 v[222:223], v[228:229], 2, v[222:223]
	s_and_saveexec_b64 s[76:77], s[42:43]
	global_store_dwordx4 v[222:223], v[68:71], off
	global_store_dwordx4 v[222:223], v[64:67], off offset:16
	s_or_b64 exec, exec, s[76:77]
	v_add_u32_e32 v228, 128, v199
	v_mov_b64_e32 v[224:225], s[12:13]
	s_movk_i32 s80, 0x1600
	v_mad_i64_i32 v[224:225], s[78:79], v228, s80, v[224:225]
	v_add_u32_e32 v228, 128, v240
	v_mov_b32_e32 v229, 0
	v_lshl_add_u64 v[224:225], v[228:229], 0, v[224:225]
	v_fma_f32 v160, v100, v48, v124
	v_fma_f32 v161, v101, v49, v125
	v_fma_f32 v162, v102, v50, v126
	v_fma_f32 v163, v103, v51, v127
	v_fma_f32 v164, v120, v44, v72
	v_fma_f32 v165, v121, v45, v73
	v_fma_f32 v166, v122, v46, v74
	v_fma_f32 v167, v123, v47, v75
	v_fmac_f32_dpp v160, v48, v88 row_shr:1 row_mask:0xf bank_mask:0xf
	v_fmac_f32_dpp v161, v49, v89 row_shr:1 row_mask:0xf bank_mask:0xf
	v_fmac_f32_dpp v162, v50, v90 row_shr:1 row_mask:0xf bank_mask:0xf
	v_fmac_f32_dpp v163, v51, v91 row_shr:1 row_mask:0xf bank_mask:0xf
	v_fmac_f32_dpp v164, v44, v116 row_shr:1 row_mask:0xf bank_mask:0xf
	v_fmac_f32_dpp v165, v45, v117 row_shr:1 row_mask:0xf bank_mask:0xf
	v_fmac_f32_dpp v166, v46, v118 row_shr:1 row_mask:0xf bank_mask:0xf
	v_fmac_f32_dpp v167, v47, v119 row_shr:1 row_mask:0xf bank_mask:0xf
	v_fmac_f32_dpp v160, v48, v84 row_shr:2 row_mask:0xf bank_mask:0xf
	v_fmac_f32_dpp v161, v49, v85 row_shr:2 row_mask:0xf bank_mask:0xf
	v_fmac_f32_dpp v162, v50, v86 row_shr:2 row_mask:0xf bank_mask:0xf
	v_fmac_f32_dpp v163, v51, v87 row_shr:2 row_mask:0xf bank_mask:0xf
	v_fmac_f32_dpp v164, v44, v104 row_shr:2 row_mask:0xf bank_mask:0xf
	v_fmac_f32_dpp v165, v45, v105 row_shr:2 row_mask:0xf bank_mask:0xf
	v_fmac_f32_dpp v166, v46, v106 row_shr:2 row_mask:0xf bank_mask:0xf
	v_fmac_f32_dpp v167, v47, v107 row_shr:2 row_mask:0xf bank_mask:0xf
	v_mul_f32_e32 v168, 0xbfb8aa3b, v160
	v_mul_f32_e32 v169, 0xbfb8aa3b, v161
	v_mul_f32_e32 v170, 0xbfb8aa3b, v162
	v_mul_f32_e32 v171, 0xbfb8aa3b, v163
	v_exp_f32_e32 v168, v168
	v_exp_f32_e32 v169, v169
	v_exp_f32_e32 v170, v170
	v_exp_f32_e32 v171, v171
	v_add_f32_e32 v168, 1.0, v168
	v_add_f32_e32 v169, 1.0, v169
	v_add_f32_e32 v170, 1.0, v170
	v_add_f32_e32 v171, 1.0, v171
	v_rcp_f32_e32 v168, v168
	v_rcp_f32_e32 v169, v169
	v_rcp_f32_e32 v170, v170
	v_rcp_f32_e32 v171, v171
	v_mov_b64_e32 v[174:175], v[224:225]
	v_mul_f32_e32 v160, v160, v168
	v_mul_f32_e32 v161, v161, v169
	v_mul_f32_e32 v162, v162, v170
	v_mul_f32_e32 v163, v163, v171
	v_mul_f32_e32 v160, v164, v160
	v_mul_f32_e32 v161, v165, v161
	v_mul_f32_e32 v162, v166, v162
	v_mul_f32_e32 v163, v167, v163
	v_cvt_pk_bf16_f32 v172, v160, v161
	v_cvt_pk_bf16_f32 v173, v162, v163
	s_and_saveexec_b64 s[76:77], s[38:39]
	global_store_dwordx2 v[174:175], v[172:173], off
	s_or_b64 exec, exec, s[76:77]
	s_ashr_i32 s80, s71, 6
	s_lshl_b32 s80, s80, 2
	s_add_i32 s80, s80, 8
	v_add_u32_e32 v226, s80, v188
	v_mov_b64_e32 v[174:175], s[8:9]
	s_movk_i32 s80, 0x5800
	v_mad_i64_i32 v[174:175], s[78:79], v226, s80, v[174:175]
	v_lshl_add_u64 v[174:175], v[228:229], 2, v[174:175]
	s_and_saveexec_b64 s[76:77], s[40:41]
	global_store_dwordx4 v[174:175], v[48:51], off
	global_store_dwordx4 v[174:175], v[44:47], off offset:16
	s_or_b64 exec, exec, s[76:77]
	v_fma_f32 v208, v100, v24, v124
	v_fma_f32 v209, v101, v25, v125
	v_fma_f32 v210, v102, v26, v126
	v_fma_f32 v211, v103, v27, v127
	v_fma_f32 v212, v120, v20, v72
	v_fma_f32 v213, v121, v21, v73
	v_fma_f32 v214, v122, v22, v74
	v_fma_f32 v215, v123, v23, v75
	v_fmac_f32_dpp v208, v24, v88 row_shr:1 row_mask:0xf bank_mask:0xf
	v_fmac_f32_dpp v209, v25, v89 row_shr:1 row_mask:0xf bank_mask:0xf
; DI float silu_fast(float x) { return x * __builtin_amdgcn_rcpf(1.f + __expf(-x)); }
; template <int CTRL> DI float dppf(float v) { return __builtin_bit_cast(float, __builtin_amdgcn_update_dpp(0, __builtin_bit_cast(int, v), CTRL, 0xf, 0xf, true)); }
; DI void Epi::fused(const f32x4 (&acc)[2][2][4][2], int pm, int pn, int wr, int wc, int fr, int fq) const {
;     ...
;             for (int m = 0; m < 4; ++m) {
;                 const f32x4 ca = acc[ai][bj][m][0], cb = acc[ai][bj][m][1];
;                 const int row = pm * 256 + ai * 128 + wr * 64 + m * 16 + fr;
;                 float o[4];
; #pragma unroll
;                 for (int e = 0; e < 4; ++e) {
;                     const float a1 = dppf<0x111>(ca[e]) + dppf<0x10F>(pa[e]), a2 = dppf<0x112>(ca[e]) + dppf<0x10E>(pa[e]);
;                     const float b1 = dppf<0x111>(cb[e]) + dppf<0x10F>(pb[e]), b2 = dppf<0x112>(cb[e]) + dppf<0x10E>(pb[e]);
;                     const float ya = fmaf(wa0[e], a2, fmaf(wa1[e], a1, fmaf(wa2[e], ca[e], ba[e])));
;                     const float yb = fmaf(wb0[e], b2, fmaf(wb1[e], b1, fmaf(wb2[e], cb[e], bb[e])));
;                     o[e] = silu_fast(ya) * yb; }
;                 if (m > 0 || fr >= 2) { u32x2 w; w.x = pk2(o[0], o[1]); w.y = pk2(o[2], o[3]); *(u32x2*)(E.d0 + (size_t)row * FFH + j0) = w; }
	v_fmac_f32_dpp v210, v26, v90 row_shr:1 row_mask:0xf bank_mask:0xf
	v_fmac_f32_dpp v211, v27, v91 row_shr:1 row_mask:0xf bank_mask:0xf
	v_fmac_f32_dpp v212, v20, v116 row_shr:1 row_mask:0xf bank_mask:0xf
	v_fmac_f32_dpp v213, v21, v117 row_shr:1 row_mask:0xf bank_mask:0xf
	v_fmac_f32_dpp v214, v22, v118 row_shr:1 row_mask:0xf bank_mask:0xf
	v_fmac_f32_dpp v215, v23, v119 row_shr:1 row_mask:0xf bank_mask:0xf
	v_fmac_f32_dpp v208, v48, v88 row_shl:15 row_mask:0xf bank_mask:0xf
	v_fmac_f32_dpp v209, v49, v89 row_shl:15 row_mask:0xf bank_mask:0xf
	v_fmac_f32_dpp v210, v50, v90 row_shl:15 row_mask:0xf bank_mask:0xf
	v_fmac_f32_dpp v211, v51, v91 row_shl:15 row_mask:0xf bank_mask:0xf
	v_fmac_f32_dpp v212, v44, v116 row_shl:15 row_mask:0xf bank_mask:0xf
	v_fmac_f32_dpp v213, v45, v117 row_shl:15 row_mask:0xf bank_mask:0xf
	v_fmac_f32_dpp v214, v46, v118 row_shl:15 row_mask:0xf bank_mask:0xf
	v_fmac_f32_dpp v215, v47, v119 row_shl:15 row_mask:0xf bank_mask:0xf
	v_fmac_f32_dpp v208, v24, v84 row_shr:2 row_mask:0xf bank_mask:0xf
	v_fmac_f32_dpp v209, v25, v85 row_shr:2 row_mask:0xf bank_mask:0xf
	v_fmac_f32_dpp v210, v26, v86 row_shr:2 row_mask:0xf bank_mask:0xf
	v_fmac_f32_dpp v211, v27, v87 row_shr:2 row_mask:0xf bank_mask:0xf
	v_fmac_f32_dpp v212, v20, v104 row_shr:2 row_mask:0xf bank_mask:0xf
	v_fmac_f32_dpp v213, v21, v105 row_shr:2 row_mask:0xf bank_mask:0xf
	v_fmac_f32_dpp v214, v22, v106 row_shr:2 row_mask:0xf bank_mask:0xf
	v_fmac_f32_dpp v215, v23, v107 row_shr:2 row_mask:0xf bank_mask:0xf
	v_fmac_f32_dpp v208, v48, v84 row_shl:14 row_mask:0xf bank_mask:0xf
	v_fmac_f32_dpp v209, v49, v85 row_shl:14 row_mask:0xf bank_mask:0xf
	v_fmac_f32_dpp v210, v50, v86 row_shl:14 row_mask:0xf bank_mask:0xf
	v_fmac_f32_dpp v211, v51, v87 row_shl:14 row_mask:0xf bank_mask:0xf
	v_fmac_f32_dpp v212, v44, v104 row_shl:14 row_mask:0xf bank_mask:0xf
	v_fmac_f32_dpp v213, v45, v105 row_shl:14 row_mask:0xf bank_mask:0xf
	v_fmac_f32_dpp v214, v46, v106 row_shl:14 row_mask:0xf bank_mask:0xf
	v_fmac_f32_dpp v215, v47, v107 row_shl:14 row_mask:0xf bank_mask:0xf
	v_mul_f32_e32 v216, 0xbfb8aa3b, v208
	v_mul_f32_e32 v217, 0xbfb8aa3b, v209
	v_mul_f32_e32 v218, 0xbfb8aa3b, v210
	v_mul_f32_e32 v219, 0xbfb8aa3b, v211
	v_exp_f32_e32 v216, v216
	v_exp_f32_e32 v217, v217
	v_exp_f32_e32 v218, v218
	v_exp_f32_e32 v219, v219
	v_add_f32_e32 v216, 1.0, v216
	v_add_f32_e32 v217, 1.0, v217
	v_add_f32_e32 v218, 1.0, v218
	v_add_f32_e32 v219, 1.0, v219
	v_rcp_f32_e32 v216, v216
	v_rcp_f32_e32 v217, v217
	v_rcp_f32_e32 v218, v218
	v_rcp_f32_e32 v219, v219
	s_mov_b32 s80, 0x16000
	s_mov_b32 s81, 0
	v_lshl_add_u64 v[222:223], v[224:225], 0, s[80:81]
	v_mul_f32_e32 v208, v208, v216
	v_mul_f32_e32 v209, v209, v217
	v_mul_f32_e32 v210, v210, v218
	v_mul_f32_e32 v211, v211, v219
	v_mul_f32_e32 v208, v212, v208
	v_mul_f32_e32 v209, v213, v209
	v_mul_f32_e32 v210, v214, v210
	v_mul_f32_e32 v211, v215, v211
	v_cvt_pk_bf16_f32 v220, v208, v209
	v_cvt_pk_bf16_f32 v221, v210, v211
	global_store_dwordx2 v[222:223], v[220:221], off
	v_fma_f32 v160, v100, v28, v124
	v_fma_f32 v161, v101, v29, v125
	v_fma_f32 v162, v102, v30, v126
	v_fma_f32 v163, v103, v31, v127
	v_fma_f32 v164, v120, v32, v72
	v_fma_f32 v165, v121, v33, v73
	v_fma_f32 v166, v122, v34, v74
	v_fma_f32 v167, v123, v35, v75
	v_fmac_f32_dpp v160, v28, v88 row_shr:1 row_mask:0xf bank_mask:0xf
	v_fmac_f32_dpp v161, v29, v89 row_shr:1 row_mask:0xf bank_mask:0xf
	v_fmac_f32_dpp v162, v30, v90 row_shr:1 row_mask:0xf bank_mask:0xf
	v_fmac_f32_dpp v163, v31, v91 row_shr:1 row_mask:0xf bank_mask:0xf
	v_fmac_f32_dpp v164, v32, v116 row_shr:1 row_mask:0xf bank_mask:0xf
	v_fmac_f32_dpp v165, v33, v117 row_shr:1 row_mask:0xf bank_mask:0xf
	v_fmac_f32_dpp v166, v34, v118 row_shr:1 row_mask:0xf bank_mask:0xf
	v_fmac_f32_dpp v167, v35, v119 row_shr:1 row_mask:0xf bank_mask:0xf
	v_fmac_f32_dpp v160, v24, v88 row_shl:15 row_mask:0xf bank_mask:0xf
	v_fmac_f32_dpp v161, v25, v89 row_shl:15 row_mask:0xf bank_mask:0xf
	v_fmac_f32_dpp v162, v26, v90 row_shl:15 row_mask:0xf bank_mask:0xf
	v_fmac_f32_dpp v163, v27, v91 row_shl:15 row_mask:0xf bank_mask:0xf
	v_fmac_f32_dpp v164, v20, v116 row_shl:15 row_mask:0xf bank_mask:0xf
	v_fmac_f32_dpp v165, v21, v117 row_shl:15 row_mask:0xf bank_mask:0xf
	v_fmac_f32_dpp v166, v22, v118 row_shl:15 row_mask:0xf bank_mask:0xf
	v_fmac_f32_dpp v167, v23, v119 row_shl:15 row_mask:0xf bank_mask:0xf
	v_fmac_f32_dpp v160, v28, v84 row_shr:2 row_mask:0xf bank_mask:0xf
	v_fmac_f32_dpp v161, v29, v85 row_shr:2 row_mask:0xf bank_mask:0xf
	v_fmac_f32_dpp v162, v30, v86 row_shr:2 row_mask:0xf bank_mask:0xf
	v_fmac_f32_dpp v163, v31, v87 row_shr:2 row_mask:0xf bank_mask:0xf
	v_fmac_f32_dpp v164, v32, v104 row_shr:2 row_mask:0xf bank_mask:0xf
	v_fmac_f32_dpp v165, v33, v105 row_shr:2 row_mask:0xf bank_mask:0xf
	v_fmac_f32_dpp v166, v34, v106 row_shr:2 row_mask:0xf bank_mask:0xf
	v_fmac_f32_dpp v167, v35, v107 row_shr:2 row_mask:0xf bank_mask:0xf
	v_fmac_f32_dpp v160, v24, v84 row_shl:14 row_mask:0xf bank_mask:0xf
	v_fmac_f32_dpp v161, v25, v85 row_shl:14 row_mask:0xf bank_mask:0xf
	v_fmac_f32_dpp v162, v26, v86 row_shl:14 row_mask:0xf bank_mask:0xf
; DI float silu_fast(float x) { return x * __builtin_amdgcn_rcpf(1.f + __expf(-x)); }
; template <int CTRL> DI float dppf(float v) { return __builtin_bit_cast(float, __builtin_amdgcn_update_dpp(0, __builtin_bit_cast(int, v), CTRL, 0xf, 0xf, true)); }
; DI void Epi::fused(const f32x4 (&acc)[2][2][4][2], int pm, int pn, int wr, int wc, int fr, int fq) const {
;     ...
;             for (int m = 0; m < 4; ++m) {
;                 const f32x4 ca = acc[ai][bj][m][0], cb = acc[ai][bj][m][1];
;                 const int row = pm * 256 + ai * 128 + wr * 64 + m * 16 + fr;
;                 float o[4];
; #pragma unroll
;                 for (int e = 0; e < 4; ++e) {
;                     const float a1 = dppf<0x111>(ca[e]) + dppf<0x10F>(pa[e]), a2 = dppf<0x112>(ca[e]) + dppf<0x10E>(pa[e]);
;                     const float b1 = dppf<0x111>(cb[e]) + dppf<0x10F>(pb[e]), b2 = dppf<0x112>(cb[e]) + dppf<0x10E>(pb[e]);
;                     const float ya = fmaf(wa0[e], a2, fmaf(wa1[e], a1, fmaf(wa2[e], ca[e], ba[e])));
;                     const float yb = fmaf(wb0[e], b2, fmaf(wb1[e], b1, fmaf(wb2[e], cb[e], bb[e])));
;                     o[e] = silu_fast(ya) * yb; }
;                 if (m > 0 || fr >= 2) { u32x2 w; w.x = pk2(o[0], o[1]); w.y = pk2(o[2], o[3]); *(u32x2*)(E.d0 + (size_t)row * FFH + j0) = w; }
;                 if ((m == 0 && fr < 2) || (m == 3 && fr >= 14)) { float* hb = E.f0 + ((size_t)(row >> 6) * 4 + (m == 0 ? fr : fr - 12)) * FF2 + ncol; *(f32x4*)hb = ca; *(f32x4*)(hb + 4) = cb; }
	v_fmac_f32_dpp v163, v27, v87 row_shl:14 row_mask:0xf bank_mask:0xf
	v_fmac_f32_dpp v164, v20, v104 row_shl:14 row_mask:0xf bank_mask:0xf
	v_fmac_f32_dpp v165, v21, v105 row_shl:14 row_mask:0xf bank_mask:0xf
	v_fmac_f32_dpp v166, v22, v106 row_shl:14 row_mask:0xf bank_mask:0xf
	v_fmac_f32_dpp v167, v23, v107 row_shl:14 row_mask:0xf bank_mask:0xf
	v_mul_f32_e32 v168, 0xbfb8aa3b, v160
	v_mul_f32_e32 v169, 0xbfb8aa3b, v161
	v_mul_f32_e32 v170, 0xbfb8aa3b, v162
	v_mul_f32_e32 v171, 0xbfb8aa3b, v163
	v_exp_f32_e32 v168, v168
	v_exp_f32_e32 v169, v169
	v_exp_f32_e32 v170, v170
	v_exp_f32_e32 v171, v171
	v_add_f32_e32 v168, 1.0, v168
	v_add_f32_e32 v169, 1.0, v169
	v_add_f32_e32 v170, 1.0, v170
	v_add_f32_e32 v171, 1.0, v171
	v_rcp_f32_e32 v168, v168
	v_rcp_f32_e32 v169, v169
	v_rcp_f32_e32 v170, v170
	v_rcp_f32_e32 v171, v171
	s_mov_b32 s80, 0x2c000
	s_mov_b32 s81, 0
	v_lshl_add_u64 v[174:175], v[224:225], 0, s[80:81]
	v_mul_f32_e32 v160, v160, v168
	v_mul_f32_e32 v161, v161, v169
	v_mul_f32_e32 v162, v162, v170
	v_mul_f32_e32 v163, v163, v171
	v_mul_f32_e32 v160, v164, v160
	v_mul_f32_e32 v161, v165, v161
	v_mul_f32_e32 v162, v166, v162
	v_mul_f32_e32 v163, v167, v163
	v_cvt_pk_bf16_f32 v172, v160, v161
	v_cvt_pk_bf16_f32 v173, v162, v163
	global_store_dwordx2 v[174:175], v[172:173], off
	v_fma_f32 v208, v100, v8, v124
	v_fma_f32 v209, v101, v9, v125
	v_fma_f32 v210, v102, v10, v126
	v_fma_f32 v211, v103, v11, v127
	v_fma_f32 v212, v120, v4, v72
	v_fma_f32 v213, v121, v5, v73
	v_fma_f32 v214, v122, v6, v74
	v_fma_f32 v215, v123, v7, v75
	v_fmac_f32_dpp v208, v8, v88 row_shr:1 row_mask:0xf bank_mask:0xf
	v_fmac_f32_dpp v209, v9, v89 row_shr:1 row_mask:0xf bank_mask:0xf
	v_fmac_f32_dpp v210, v10, v90 row_shr:1 row_mask:0xf bank_mask:0xf
	v_fmac_f32_dpp v211, v11, v91 row_shr:1 row_mask:0xf bank_mask:0xf
	v_fmac_f32_dpp v212, v4, v116 row_shr:1 row_mask:0xf bank_mask:0xf
	v_fmac_f32_dpp v213, v5, v117 row_shr:1 row_mask:0xf bank_mask:0xf
	v_fmac_f32_dpp v214, v6, v118 row_shr:1 row_mask:0xf bank_mask:0xf
	v_fmac_f32_dpp v215, v7, v119 row_shr:1 row_mask:0xf bank_mask:0xf
	v_fmac_f32_dpp v208, v28, v88 row_shl:15 row_mask:0xf bank_mask:0xf
	v_fmac_f32_dpp v209, v29, v89 row_shl:15 row_mask:0xf bank_mask:0xf
	v_fmac_f32_dpp v210, v30, v90 row_shl:15 row_mask:0xf bank_mask:0xf
	v_fmac_f32_dpp v211, v31, v91 row_shl:15 row_mask:0xf bank_mask:0xf
	v_fmac_f32_dpp v212, v32, v116 row_shl:15 row_mask:0xf bank_mask:0xf
	v_fmac_f32_dpp v213, v33, v117 row_shl:15 row_mask:0xf bank_mask:0xf
	v_fmac_f32_dpp v214, v34, v118 row_shl:15 row_mask:0xf bank_mask:0xf
	v_fmac_f32_dpp v215, v35, v119 row_shl:15 row_mask:0xf bank_mask:0xf
	v_fmac_f32_dpp v208, v8, v84 row_shr:2 row_mask:0xf bank_mask:0xf
	v_fmac_f32_dpp v209, v9, v85 row_shr:2 row_mask:0xf bank_mask:0xf
	v_fmac_f32_dpp v210, v10, v86 row_shr:2 row_mask:0xf bank_mask:0xf
	v_fmac_f32_dpp v211, v11, v87 row_shr:2 row_mask:0xf bank_mask:0xf
	v_fmac_f32_dpp v212, v4, v104 row_shr:2 row_mask:0xf bank_mask:0xf
	v_fmac_f32_dpp v213, v5, v105 row_shr:2 row_mask:0xf bank_mask:0xf
	v_fmac_f32_dpp v214, v6, v106 row_shr:2 row_mask:0xf bank_mask:0xf
	v_fmac_f32_dpp v215, v7, v107 row_shr:2 row_mask:0xf bank_mask:0xf
	v_fmac_f32_dpp v208, v28, v84 row_shl:14 row_mask:0xf bank_mask:0xf
	v_fmac_f32_dpp v209, v29, v85 row_shl:14 row_mask:0xf bank_mask:0xf
	v_fmac_f32_dpp v210, v30, v86 row_shl:14 row_mask:0xf bank_mask:0xf
	v_fmac_f32_dpp v211, v31, v87 row_shl:14 row_mask:0xf bank_mask:0xf
	v_fmac_f32_dpp v212, v32, v104 row_shl:14 row_mask:0xf bank_mask:0xf
	v_fmac_f32_dpp v213, v33, v105 row_shl:14 row_mask:0xf bank_mask:0xf
	v_fmac_f32_dpp v214, v34, v106 row_shl:14 row_mask:0xf bank_mask:0xf
	v_fmac_f32_dpp v215, v35, v107 row_shl:14 row_mask:0xf bank_mask:0xf
	v_mul_f32_e32 v216, 0xbfb8aa3b, v208
	v_mul_f32_e32 v217, 0xbfb8aa3b, v209
	v_mul_f32_e32 v218, 0xbfb8aa3b, v210
	v_mul_f32_e32 v219, 0xbfb8aa3b, v211
	v_exp_f32_e32 v216, v216
	v_exp_f32_e32 v217, v217
	v_exp_f32_e32 v218, v218
	v_exp_f32_e32 v219, v219
	v_add_f32_e32 v216, 1.0, v216
	v_add_f32_e32 v217, 1.0, v217
	v_add_f32_e32 v218, 1.0, v218
	v_add_f32_e32 v219, 1.0, v219
	v_rcp_f32_e32 v216, v216
	v_rcp_f32_e32 v217, v217
	v_rcp_f32_e32 v218, v218
	v_rcp_f32_e32 v219, v219
	s_mov_b32 s80, 0x42000
	s_mov_b32 s81, 0
	v_lshl_add_u64 v[222:223], v[224:225], 0, s[80:81]
	v_mul_f32_e32 v208, v208, v216
	v_mul_f32_e32 v209, v209, v217
	v_mul_f32_e32 v210, v210, v218
	v_mul_f32_e32 v211, v211, v219
	v_mul_f32_e32 v208, v212, v208
	v_mul_f32_e32 v209, v213, v209
	v_mul_f32_e32 v210, v214, v210
	v_mul_f32_e32 v211, v215, v211
	v_cvt_pk_bf16_f32 v220, v208, v209
	v_cvt_pk_bf16_f32 v221, v210, v211
	global_store_dwordx2 v[222:223], v[220:221], off
	s_ashr_i32 s80, s71, 6
	s_lshl_b32 s80, s80, 2
	s_add_i32 s80, s80, 8
	v_add_u32_e32 v226, s80, v190
	v_mov_b64_e32 v[222:223], s[8:9]
	s_movk_i32 s80, 0x5800
	v_mad_i64_i32 v[222:223], s[78:79], v226, s80, v[222:223]
	v_lshl_add_u64 v[222:223], v[228:229], 2, v[222:223]
	s_and_saveexec_b64 s[76:77], s[42:43]
	global_store_dwordx4 v[222:223], v[8:11], off
	global_store_dwordx4 v[222:223], v[4:7], off offset:16
	s_or_b64 exec, exec, s[76:77]
